# P1: epilogue row-scale loads issued inside the last K-step (even-tile A staging set moved to v2-v17)
# baseline (speedup 1.0000x reference)
;     ...
;   const int srow = tid >> 3, skc = tid & 7;
;   const u16* Ag = A + (size_t)(m0 + srow) * K + skc * 8;
;   const u16* Bg[4];
; #pragma unroll
;   for (int i = 0; i < 4; ++i) { int n = n0 + srow + 64 * i; n = n < nmax ? n : nmax - 1; Bg[i] = Bt + (size_t)n * K + skc * 8; }
;   const int nk = nk_override ? nk_override : K / 64;
; #pragma unroll
;   for (int i = 0; i < 4; ++i) { ra[i] = *(const u32x4*)(Ag + (size_t)(64 * i) * K); rb[i] = *(const u32x4*)(Bg[i]); }
; #pragma unroll
;   for (int i = 0; i < 4; ++i) { *(u32x4*)(As0 + (srow + 64 * i) * LD + skc * 8) = ra[i]; *(u32x4*)(Bs0 + (srow + 64 * i) * LD + skc * 8) = rb[i]; }
;   if (nk > 1) {
; #pragma unroll
;     for (int i = 0; i < 4; ++i) { ra[i] = *(const u32x4*)(Ag + (size_t)(64 * i) * K + 64); rb[i] = *(const u32x4*)(Bg[i] + 64); }
;   }
;   for (int kt = 0; kt < nk; ++kt) {
;     __syncthreads();
;     if (kt + 1 < nk) {
;       u16* aw = As0 + ((kt + 1) & 1) * 256 * LD;
;       u16* bw = Bs0 + ((kt + 1) & 1) * 256 * LD;
; #pragma unroll
;       for (int i = 0; i < 4; ++i) { *(u32x4*)(aw + (srow + 64 * i) * LD + skc * 8) = ra[i]; *(u32x4*)(bw + (srow + 64 * i) * LD + skc * 8) = rb[i]; }
;     }
;     if (kt + 2 < nk) {
; #pragma unroll
;       for (int i = 0; i < 4; ++i) { ra[i] = *(const u32x4*)(Ag + (size_t)(64 * i) * K + (kt + 2) * 64); rb[i] = *(const u32x4*)(Bg[i] + (kt + 2) * 64); }
;     }
;     ...
;   for (int Lx = jx; Lx < (NMT / 8) * NNT; Lx += nbx) {
;     const int grp = Lx / (2 * NNT), gi = Lx % (2 * NNT);
;     const int mt = xcd * (NMT / 8) + 2 * grp + (gi & 1), nt = gi >> 1;
;     gemm_tile(p.xb, p.winT, DM, mt * 256, nt * 256, INW, lds, [&](f32x16 (&acc)[2][4], int m0, int n0, int wr, int wc, int l31, int h) {
.LBB0_107:
	s_lshl_b32 s34, s34, 1
	s_add_i32 s34, s34, s40
	s_and_b32 s30, s35, 1
	s_or_b32 s30, s34, s30
	s_lshl_b32 s59, s62, 8
	v_ashrrev_i32_e32 v42, 3, v227
	s_lshl_b32 s35, s30, 8
	s_waitcnt vmcnt(3)
	v_add_u32_e32 v10, s59, v42
	s_waitcnt vmcnt(0)
	v_add_u32_e32 v4, s35, v42
	v_lshlrev_b32_e32 v2, 4, v227
	v_min_i32_e32 v8, 0x107f, v10
	v_ashrrev_i32_e32 v5, 31, v4
	v_and_b32_e32 v2, 0x70, v2
	v_ashrrev_i32_e32 v9, 31, v8
	v_lshlrev_b64 v[4:5], 11, v[4:5]
	s_waitcnt lgkmcnt(0)
	v_lshl_add_u64 v[6:7], s[18:19], 0, v[2:3]
	v_lshlrev_b64 v[8:9], 11, v[8:9]
	v_lshl_add_u64 v[228:229], v[6:7], 0, v[8:9]
	v_min_i32_e32 v8, 0x103f, v10
	v_lshl_add_u64 v[4:5], s[16:17], 0, v[4:5]
	v_ashrrev_i32_e32 v9, 31, v8
	v_lshl_add_u64 v[230:231], v[4:5], 0, v[2:3]
	v_lshlrev_b64 v[8:9], 11, v[8:9]
	v_add_co_u32_e32 v232, vcc, s42, v230
	v_lshl_add_u64 v[36:37], v[6:7], 0, v[8:9]
	v_min_i32_e32 v8, 0xfff, v10
	v_addc_co_u32_e32 v233, vcc, 0, v231, vcc
	v_ashrrev_i32_e32 v9, 31, v8
	v_add_co_u32_e32 v16, vcc, s42, v36
	v_lshlrev_b64 v[8:9], 11, v[8:9]
	s_nop 0
	v_addc_co_u32_e32 v17, vcc, 0, v37, vcc
	v_lshl_add_u64 v[38:39], v[6:7], 0, v[8:9]
	v_min_i32_e32 v8, 0xfbf, v10
	v_add_co_u32_e32 v68, vcc, s43, v230
	v_ashrrev_i32_e32 v9, 31, v8
	s_nop 0
	v_addc_co_u32_e32 v69, vcc, 0, v231, vcc
	v_lshlrev_b64 v[8:9], 11, v[8:9]
	v_add_co_u32_e32 v24, vcc, s43, v38
	v_lshl_add_u64 v[40:41], v[6:7], 0, v[8:9]
	global_load_dwordx4 v[4:7], v[230:231], off
	global_load_dwordx4 v[8:11], v[228:229], off
	v_addc_co_u32_e32 v25, vcc, 0, v39, vcc
	global_load_dwordx4 v[16:19], v[16:17], off
	v_add_co_u32_e32 v28, vcc, s44, v40
	global_load_dwordx4 v[24:27], v[24:25], off
	s_nop 0
	v_addc_co_u32_e32 v29, vcc, 0, v41, vcc
	global_load_dwordx4 v[28:31], v[28:29], off
	v_add_co_u32_e32 v70, vcc, s44, v230
	global_load_dwordx4 v[12:15], v[232:233], off
	global_load_dwordx4 v[20:23], v[68:69], off
	v_addc_co_u32_e32 v71, vcc, 0, v231, vcc
	global_load_dwordx4 v[32:35], v[70:71], off
	v_mul_lo_u32 v42, v42, s46
	v_add3_u32 v251, s45, v2, v42
	v_add3_u32 v250, 0, v2, v42
	v_lshl_add_u64 v[238:239], v[36:37], 0, s[24:25]
	v_lshl_add_u64 v[234:235], v[38:39], 0, s[26:27]
	v_lshl_add_u64 v[236:237], v[40:41], 0, s[28:29]
	global_load_dwordx4 v[36:39], v[228:229], off offset:128
	global_load_dwordx4 v[40:43], v[238:239], off offset:128
	global_load_dwordx4 v[44:47], v[234:235], off offset:128
	global_load_dwordx4 v[48:51], v[236:237], off offset:128
	global_load_dwordx4 v[52:55], v[230:231], off offset:128
	global_load_dwordx4 v[56:59], v[232:233], off offset:128
	global_load_dwordx4 v[60:63], v[68:69], off offset:128
	global_load_dwordx4 v[64:67], v[70:71], off offset:128
	s_ashr_i32 s36, s60, 6
	s_bfe_u32 s37, s36, 0x10001
	s_ashr_i32 s38, s60, 8
	s_and_b64 s[30:31], s[6:7], exec
	s_cselect_b32 s37, s37, s38
	s_xor_b64 s[6:7], s[6:7], -1
	s_cmp_lt_i32 s36, 4
	v_and_b32_e32 v225, 31, v227
	s_cselect_b64 s[30:31], -1, 0
	s_lshl_b32 s36, s37, 7
	v_bfe_u32 v247, v227, 5, 1
	v_or_b32_e32 v2, s36, v225
	v_mul_lo_u32 v2, v2, s46
	v_lshlrev_b32_e32 v226, 4, v247
	s_lshl_b32 s61, s20, 6
	v_add3_u32 v248, 0, v2, v226
	v_or_b32_e32 v2, s61, v225
	v_mul_lo_u32 v2, v2, s46
	s_or_b64 s[30:31], s[6:7], s[30:31]
	v_add3_u32 v249, s45, v2, v226
	s_waitcnt vmcnt(14)
	ds_write_b128 v251, v[8:11]
	s_waitcnt vmcnt(13)
	ds_write_b128 v251, v[16:19] offset:9216
	s_waitcnt vmcnt(12)
	ds_write_b128 v251, v[24:27] offset:18432
	s_waitcnt vmcnt(11)
	ds_write_b128 v251, v[28:31] offset:27648
	ds_write_b128 v250, v[4:7]
	s_waitcnt vmcnt(10)
	ds_write_b128 v250, v[12:15] offset:9216
	s_waitcnt vmcnt(9)
	ds_write_b128 v250, v[20:23] offset:18432
	s_waitcnt vmcnt(8)
	ds_write_b128 v250, v[32:35] offset:27648
	s_waitcnt lgkmcnt(0)
	s_barrier
	s_andn2_b64 vcc, exec, s[30:31]
	s_cbranch_vccnz .Lp1_stage_only
	v_lshrrev_b32_e32 v227, 3, v223
	v_lshlrev_b32_e32 v227, 11, v227
	v_lshlrev_b32_e32 v2, 4, v223
	v_and_b32_e32 v2, 0x70, v2
	v_or_b32_e32 v227, v227, v2
	s_lshl_b32 s6, s35, 11
	s_add_u32 s74, s16, s6
	s_addc_u32 s75, s17, 0
	s_add_u32 s76, s74, 0x20000
	s_addc_u32 s77, s75, 0
	s_add_u32 s78, s74, 0x40000
	s_addc_u32 s79, s75, 0
	s_add_u32 s80, s74, 0x60000
	s_addc_u32 s81, s75, 0
	s_lshl_b32 s6, s59, 11
	s_add_u32 s82, s18, s6
	s_addc_u32 s83, s19, 0
	s_add_u32 s84, s82, 0x20000
	s_addc_u32 s85, s83, 0
	s_add_u32 s86, s82, 0x40000
	s_addc_u32 s87, s83, 0
	s_add_u32 s92, s82, 0x60000
	s_addc_u32 s93, s83, 0
	global_load_dwordx4 v[2:5], v227, s[74:75] offset:256
	global_load_dwordx4 v[162:165], v227, s[82:83] offset:256
	global_load_dwordx4 v[6:9], v227, s[76:77] offset:256
	global_load_dwordx4 v[166:169], v227, s[84:85] offset:256
	global_load_dwordx4 v[10:13], v227, s[78:79] offset:256
	global_load_dwordx4 v[170:173], v227, s[86:87] offset:256
	global_load_dwordx4 v[14:17], v227, s[80:81] offset:256
	global_load_dwordx4 v[174:177], v227, s[92:93] offset:256
	global_load_dwordx4 v[146:149], v227, s[74:75] offset:384
	global_load_dwordx4 v[178:181], v227, s[82:83] offset:384
	global_load_dwordx4 v[150:153], v227, s[76:77] offset:384
	global_load_dwordx4 v[182:185], v227, s[84:85] offset:384
	global_load_dwordx4 v[154:157], v227, s[78:79] offset:384
	global_load_dwordx4 v[186:189], v227, s[86:87] offset:384
	global_load_dwordx4 v[158:161], v227, s[80:81] offset:384
	global_load_dwordx4 v[190:193], v227, s[92:93] offset:384
	s_waitcnt vmcnt(23)
	ds_write_b128 v251, v[36:39] offset:36864
	s_waitcnt vmcnt(22)
	ds_write_b128 v251, v[40:43] offset:46080
	s_waitcnt vmcnt(21)
	ds_write_b128 v251, v[44:47] offset:55296
	s_waitcnt vmcnt(20)
	ds_write_b128 v251, v[48:51] offset:64512
	s_waitcnt vmcnt(19)
;     ...
;   for (int kt = 0; kt < nk; ++kt) {
;     __syncthreads();
;     if (kt + 1 < nk) {
;       u16* aw = As0 + ((kt + 1) & 1) * 256 * LD;
;       u16* bw = Bs0 + ((kt + 1) & 1) * 256 * LD;
; #pragma unroll
;       for (int i = 0; i < 4; ++i) { *(u32x4*)(aw + (srow + 64 * i) * LD + skc * 8) = ra[i]; *(u32x4*)(bw + (srow + 64 * i) * LD + skc * 8) = rb[i]; }
;     }
;     if (kt + 2 < nk) {
; #pragma unroll
;       for (int i = 0; i < 4; ++i) { ra[i] = *(const u32x4*)(Ag + (size_t)(64 * i) * K + (kt + 2) * 64); rb[i] = *(const u32x4*)(Bg[i] + (kt + 2) * 64); }
;     }
;     __builtin_amdgcn_sched_barrier(0);
;     const u16* as = As0 + (kt & 1) * 256 * LD + (wr * 128 + l31) * LD + h * 8;
;     const u16* bs = Bs0 + (kt & 1) * 256 * LD + (wc * 64 + l31) * LD + h * 8;
;     if (domma)
; #pragma unroll
;     for (int ks = 0; ks < 4; ++ks) {
;       bf16x8 wf[2], xf[4];
; #pragma unroll
;       for (int ct = 0; ct < 2; ++ct) wf[ct] = *(const bf16x8*)(bs + ct * 32 * LD + ks * 16);
; #pragma unroll
;       for (int tt = 0; tt < 4; ++tt) xf[tt] = *(const bf16x8*)(as + tt * 32 * LD + ks * 16);
; #pragma unroll
;       for (int ct = 0; ct < 2; ++ct)
; #pragma unroll
;         for (int tt = 0; tt < 4; ++tt) acc[ct][tt] = __builtin_amdgcn_mfma_f32_32x32x16_bf16(wf[ct], xf[tt], acc[ct][tt], 0, 0, 0);
;     }
	ds_write_b128 v250, v[52:55] offset:36864
	s_waitcnt vmcnt(18)
	ds_write_b128 v250, v[56:59] offset:46080
	s_waitcnt vmcnt(17)
	ds_write_b128 v250, v[60:63] offset:55296
	s_waitcnt vmcnt(16)
	ds_write_b128 v250, v[64:67] offset:64512
	ds_read_b128 v[194:197], v249
	ds_read_b128 v[210:213], v248
	ds_read_b128 v[198:201], v249 offset:4608
	ds_read_b128 v[214:217], v248 offset:4608
	ds_read_b128 v[228:231], v248 offset:9216
	ds_read_b128 v[232:235], v248 offset:13824
	s_waitcnt lgkmcnt(4)
	v_mfma_f32_32x32x16_bf16 v[114:129], v[194:197], v[210:213], 0
	ds_read_b128 v[202:205], v249 offset:32
	s_waitcnt lgkmcnt(4)
	v_mfma_f32_32x32x16_bf16 v[130:145], v[198:201], v[210:213], 0
	ds_read_b128 v[236:239], v248 offset:32
	s_waitcnt lgkmcnt(4)
	v_mfma_f32_32x32x16_bf16 v[82:97], v[194:197], v[214:217], 0
	ds_read_b128 v[206:209], v249 offset:4640
	v_mfma_f32_32x32x16_bf16 v[98:113], v[198:201], v[214:217], 0
	ds_read_b128 v[210:213], v248 offset:4640
	s_waitcnt lgkmcnt(5)
	v_mfma_f32_32x32x16_bf16 v[50:65], v[194:197], v[228:231], 0
	ds_read_b128 v[214:217], v248 offset:9248
	v_mfma_f32_32x32x16_bf16 v[66:81], v[198:201], v[228:231], 0
	s_waitcnt lgkmcnt(5)
	v_mfma_f32_32x32x16_bf16 v[18:33], v[194:197], v[232:235], 0
	ds_read_b128 v[228:231], v248 offset:13856
	v_mfma_f32_32x32x16_bf16 v[34:49], v[198:201], v[232:235], 0
	s_waitcnt lgkmcnt(4)
	v_mfma_f32_32x32x16_bf16 v[114:129], v[202:205], v[236:239], v[114:129]
	ds_read_b128 v[194:197], v249 offset:64
	s_waitcnt lgkmcnt(4)
	v_mfma_f32_32x32x16_bf16 v[130:145], v[206:209], v[236:239], v[130:145]
	ds_read_b128 v[232:235], v248 offset:64
	s_waitcnt lgkmcnt(4)
	v_mfma_f32_32x32x16_bf16 v[82:97], v[202:205], v[210:213], v[82:97]
	ds_read_b128 v[198:201], v249 offset:4672
	v_mfma_f32_32x32x16_bf16 v[98:113], v[206:209], v[210:213], v[98:113]
	ds_read_b128 v[236:239], v248 offset:4672
	s_waitcnt lgkmcnt(5)
	v_mfma_f32_32x32x16_bf16 v[50:65], v[202:205], v[214:217], v[50:65]
	ds_read_b128 v[210:213], v248 offset:9280
	v_mfma_f32_32x32x16_bf16 v[66:81], v[206:209], v[214:217], v[66:81]
	s_waitcnt lgkmcnt(5)
	v_mfma_f32_32x32x16_bf16 v[18:33], v[202:205], v[228:231], v[18:33]
	ds_read_b128 v[214:217], v248 offset:13888
	v_mfma_f32_32x32x16_bf16 v[34:49], v[206:209], v[228:231], v[34:49]
	s_waitcnt lgkmcnt(4)
	v_mfma_f32_32x32x16_bf16 v[114:129], v[194:197], v[232:235], v[114:129]
	ds_read_b128 v[202:205], v249 offset:96
	s_waitcnt lgkmcnt(4)
	v_mfma_f32_32x32x16_bf16 v[130:145], v[198:201], v[232:235], v[130:145]
	ds_read_b128 v[228:231], v248 offset:96
	s_waitcnt lgkmcnt(4)
	v_mfma_f32_32x32x16_bf16 v[82:97], v[194:197], v[236:239], v[82:97]
	ds_read_b128 v[206:209], v249 offset:4704
	v_mfma_f32_32x32x16_bf16 v[98:113], v[198:201], v[236:239], v[98:113]
	ds_read_b128 v[232:235], v248 offset:4704
	s_waitcnt lgkmcnt(5)
	v_mfma_f32_32x32x16_bf16 v[50:65], v[194:197], v[210:213], v[50:65]
	ds_read_b128 v[236:239], v248 offset:9312
	v_mfma_f32_32x32x16_bf16 v[66:81], v[198:201], v[210:213], v[66:81]
	s_waitcnt lgkmcnt(5)
	v_mfma_f32_32x32x16_bf16 v[18:33], v[194:197], v[214:217], v[18:33]
	ds_read_b128 v[210:213], v248 offset:13920
	v_mfma_f32_32x32x16_bf16 v[34:49], v[198:201], v[214:217], v[34:49]
	s_waitcnt lgkmcnt(4)
	v_mfma_f32_32x32x16_bf16 v[114:129], v[202:205], v[228:231], v[114:129]
	s_waitcnt lgkmcnt(3)
	v_mfma_f32_32x32x16_bf16 v[130:145], v[206:209], v[228:231], v[130:145]
	s_waitcnt lgkmcnt(2)
	v_mfma_f32_32x32x16_bf16 v[82:97], v[202:205], v[232:235], v[82:97]
	v_mfma_f32_32x32x16_bf16 v[98:113], v[206:209], v[232:235], v[98:113]
	s_waitcnt lgkmcnt(1)
	v_mfma_f32_32x32x16_bf16 v[50:65], v[202:205], v[236:239], v[50:65]
	v_mfma_f32_32x32x16_bf16 v[66:81], v[206:209], v[236:239], v[66:81]
	s_waitcnt lgkmcnt(0)
	v_mfma_f32_32x32x16_bf16 v[18:33], v[202:205], v[210:213], v[18:33]
	v_mfma_f32_32x32x16_bf16 v[34:49], v[206:209], v[210:213], v[34:49]
	s_barrier
	ds_read_b128 v[194:197], v249 offset:36864
	ds_read_b128 v[210:213], v248 offset:36864
	ds_read_b128 v[198:201], v249 offset:41472
	ds_read_b128 v[214:217], v248 offset:41472
	ds_read_b128 v[228:231], v248 offset:46080
	ds_read_b128 v[232:235], v248 offset:50688
	s_waitcnt lgkmcnt(4)
	v_mfma_f32_32x32x16_bf16 v[114:129], v[194:197], v[210:213], v[114:129]
	ds_read_b128 v[202:205], v249 offset:36896
	s_waitcnt lgkmcnt(4)
	v_mfma_f32_32x32x16_bf16 v[130:145], v[198:201], v[210:213], v[130:145]
	ds_read_b128 v[236:239], v248 offset:36896
	s_waitcnt lgkmcnt(4)
	v_mfma_f32_32x32x16_bf16 v[82:97], v[194:197], v[214:217], v[82:97]
	ds_read_b128 v[206:209], v249 offset:41504
	v_mfma_f32_32x32x16_bf16 v[98:113], v[198:201], v[214:217], v[98:113]
	ds_read_b128 v[210:213], v248 offset:41504
	s_waitcnt vmcnt(15)
	ds_write_b128 v250, v[2:5]
	s_waitcnt lgkmcnt(6)
	v_mfma_f32_32x32x16_bf16 v[50:65], v[194:197], v[228:231], v[50:65]
	ds_read_b128 v[214:217], v248 offset:46112
	v_mfma_f32_32x32x16_bf16 v[66:81], v[198:201], v[228:231], v[66:81]
	global_load_dwordx4 v[2:5], v227, s[74:75] offset:512
	s_waitcnt lgkmcnt(6)
	v_mfma_f32_32x32x16_bf16 v[18:33], v[194:197], v[232:235], v[18:33]
	ds_read_b128 v[228:231], v248 offset:50720
	s_waitcnt vmcnt(15)
	ds_write_b128 v251, v[162:165]
	v_mfma_f32_32x32x16_bf16 v[34:49], v[198:201], v[232:235], v[34:49]
	s_waitcnt lgkmcnt(6)
	v_mfma_f32_32x32x16_bf16 v[114:129], v[202:205], v[236:239], v[114:129]
	ds_read_b128 v[194:197], v249 offset:36928
	global_load_dwordx4 v[162:165], v227, s[82:83] offset:512
	s_waitcnt lgkmcnt(6)
	v_mfma_f32_32x32x16_bf16 v[130:145], v[206:209], v[236:239], v[130:145]
	ds_read_b128 v[232:235], v248 offset:36928
	s_waitcnt vmcnt(15)
	ds_write_b128 v250, v[6:9] offset:9216
	s_waitcnt lgkmcnt(7)
;     ...
;   for (int kt = 0; kt < nk; ++kt) {
;     __syncthreads();
;     if (kt + 1 < nk) {
;       u16* aw = As0 + ((kt + 1) & 1) * 256 * LD;
;       u16* bw = Bs0 + ((kt + 1) & 1) * 256 * LD;
; #pragma unroll
;       for (int i = 0; i < 4; ++i) { *(u32x4*)(aw + (srow + 64 * i) * LD + skc * 8) = ra[i]; *(u32x4*)(bw + (srow + 64 * i) * LD + skc * 8) = rb[i]; }
;     }
;     if (kt + 2 < nk) {
; #pragma unroll
;       for (int i = 0; i < 4; ++i) { ra[i] = *(const u32x4*)(Ag + (size_t)(64 * i) * K + (kt + 2) * 64); rb[i] = *(const u32x4*)(Bg[i] + (kt + 2) * 64); }
;     }
;     __builtin_amdgcn_sched_barrier(0);
;     const u16* as = As0 + (kt & 1) * 256 * LD + (wr * 128 + l31) * LD + h * 8;
;     const u16* bs = Bs0 + (kt & 1) * 256 * LD + (wc * 64 + l31) * LD + h * 8;
;     if (domma)
; #pragma unroll
;     for (int ks = 0; ks < 4; ++ks) {
;       bf16x8 wf[2], xf[4];
; #pragma unroll
;       for (int ct = 0; ct < 2; ++ct) wf[ct] = *(const bf16x8*)(bs + ct * 32 * LD + ks * 16);
; #pragma unroll
;       for (int tt = 0; tt < 4; ++tt) xf[tt] = *(const bf16x8*)(as + tt * 32 * LD + ks * 16);
; #pragma unroll
;       for (int ct = 0; ct < 2; ++ct)
; #pragma unroll
;         for (int tt = 0; tt < 4; ++tt) acc[ct][tt] = __builtin_amdgcn_mfma_f32_32x32x16_bf16(wf[ct], xf[tt], acc[ct][tt], 0, 0, 0);
;     }
;     __builtin_amdgcn_sched_barrier(0);
;   }
	v_mfma_f32_32x32x16_bf16 v[82:97], v[202:205], v[210:213], v[82:97]
	ds_read_b128 v[198:201], v249 offset:41536
	v_mfma_f32_32x32x16_bf16 v[98:113], v[206:209], v[210:213], v[98:113]
	ds_read_b128 v[236:239], v248 offset:41536
	global_load_dwordx4 v[6:9], v227, s[76:77] offset:512
	s_waitcnt lgkmcnt(7)
	v_mfma_f32_32x32x16_bf16 v[50:65], v[202:205], v[214:217], v[50:65]
	ds_read_b128 v[210:213], v248 offset:46144
	s_waitcnt vmcnt(15)
	ds_write_b128 v251, v[166:169] offset:9216
	v_mfma_f32_32x32x16_bf16 v[66:81], v[206:209], v[214:217], v[66:81]
	s_waitcnt lgkmcnt(8)
	v_mfma_f32_32x32x16_bf16 v[18:33], v[202:205], v[228:231], v[18:33]
	ds_read_b128 v[214:217], v248 offset:50752
	global_load_dwordx4 v[166:169], v227, s[84:85] offset:512
	v_mfma_f32_32x32x16_bf16 v[34:49], v[206:209], v[228:231], v[34:49]
	s_waitcnt vmcnt(15)
	ds_write_b128 v250, v[10:13] offset:18432
	s_waitcnt lgkmcnt(7)
	v_mfma_f32_32x32x16_bf16 v[114:129], v[194:197], v[232:235], v[114:129]
	ds_read_b128 v[202:205], v249 offset:36960
	s_waitcnt lgkmcnt(6)
	v_mfma_f32_32x32x16_bf16 v[130:145], v[198:201], v[232:235], v[130:145]
	ds_read_b128 v[228:231], v248 offset:36960
	global_load_dwordx4 v[10:13], v227, s[78:79] offset:512
	s_waitcnt lgkmcnt(6)
	v_mfma_f32_32x32x16_bf16 v[82:97], v[194:197], v[236:239], v[82:97]
	ds_read_b128 v[206:209], v249 offset:41568
	s_waitcnt vmcnt(15)
	ds_write_b128 v251, v[170:173] offset:18432
	v_mfma_f32_32x32x16_bf16 v[98:113], v[198:201], v[236:239], v[98:113]
	ds_read_b128 v[232:235], v248 offset:41568
	s_waitcnt lgkmcnt(8)
	v_mfma_f32_32x32x16_bf16 v[50:65], v[194:197], v[210:213], v[50:65]
	ds_read_b128 v[236:239], v248 offset:46176
	global_load_dwordx4 v[170:173], v227, s[86:87] offset:512
	v_mfma_f32_32x32x16_bf16 v[66:81], v[198:201], v[210:213], v[66:81]
	s_waitcnt vmcnt(15)
	ds_write_b128 v250, v[14:17] offset:27648
	s_waitcnt lgkmcnt(8)
	v_mfma_f32_32x32x16_bf16 v[18:33], v[194:197], v[214:217], v[18:33]
	ds_read_b128 v[210:213], v248 offset:50784
	v_mfma_f32_32x32x16_bf16 v[34:49], v[198:201], v[214:217], v[34:49]
	global_load_dwordx4 v[14:17], v227, s[80:81] offset:512
	s_waitcnt lgkmcnt(6)
	v_mfma_f32_32x32x16_bf16 v[114:129], v[202:205], v[228:231], v[114:129]
	s_waitcnt vmcnt(15)
	ds_write_b128 v251, v[174:177] offset:27648
	s_waitcnt lgkmcnt(6)
	v_mfma_f32_32x32x16_bf16 v[130:145], v[206:209], v[228:231], v[130:145]
	s_waitcnt lgkmcnt(4)
	v_mfma_f32_32x32x16_bf16 v[82:97], v[202:205], v[232:235], v[82:97]
	global_load_dwordx4 v[174:177], v227, s[92:93] offset:512
	v_mfma_f32_32x32x16_bf16 v[98:113], v[206:209], v[232:235], v[98:113]
	s_waitcnt lgkmcnt(3)
	v_mfma_f32_32x32x16_bf16 v[50:65], v[202:205], v[236:239], v[50:65]
	v_mfma_f32_32x32x16_bf16 v[66:81], v[206:209], v[236:239], v[66:81]
	s_waitcnt lgkmcnt(1)
	v_mfma_f32_32x32x16_bf16 v[18:33], v[202:205], v[210:213], v[18:33]
	v_mfma_f32_32x32x16_bf16 v[34:49], v[206:209], v[210:213], v[34:49]
	s_waitcnt lgkmcnt(0)
	s_barrier
	ds_read_b128 v[194:197], v249
	ds_read_b128 v[210:213], v248
	ds_read_b128 v[198:201], v249 offset:4608
	ds_read_b128 v[214:217], v248 offset:4608
	ds_read_b128 v[228:231], v248 offset:9216
	ds_read_b128 v[232:235], v248 offset:13824
	s_waitcnt lgkmcnt(4)
	v_mfma_f32_32x32x16_bf16 v[114:129], v[194:197], v[210:213], v[114:129]
	ds_read_b128 v[202:205], v249 offset:32
	s_waitcnt lgkmcnt(4)
	v_mfma_f32_32x32x16_bf16 v[130:145], v[198:201], v[210:213], v[130:145]
	ds_read_b128 v[236:239], v248 offset:32
	s_waitcnt lgkmcnt(4)
	v_mfma_f32_32x32x16_bf16 v[82:97], v[194:197], v[214:217], v[82:97]
	ds_read_b128 v[206:209], v249 offset:4640
	v_mfma_f32_32x32x16_bf16 v[98:113], v[198:201], v[214:217], v[98:113]
	ds_read_b128 v[210:213], v248 offset:4640
	s_waitcnt vmcnt(15)
	ds_write_b128 v250, v[146:149] offset:36864
	s_waitcnt lgkmcnt(6)
	v_mfma_f32_32x32x16_bf16 v[50:65], v[194:197], v[228:231], v[50:65]
	ds_read_b128 v[214:217], v248 offset:9248
	v_mfma_f32_32x32x16_bf16 v[66:81], v[198:201], v[228:231], v[66:81]
	global_load_dwordx4 v[146:149], v227, s[74:75] offset:640
	s_waitcnt lgkmcnt(6)
	v_mfma_f32_32x32x16_bf16 v[18:33], v[194:197], v[232:235], v[18:33]
	ds_read_b128 v[228:231], v248 offset:13856
	s_waitcnt vmcnt(15)
	ds_write_b128 v251, v[178:181] offset:36864
	v_mfma_f32_32x32x16_bf16 v[34:49], v[198:201], v[232:235], v[34:49]
	s_waitcnt lgkmcnt(6)
	v_mfma_f32_32x32x16_bf16 v[114:129], v[202:205], v[236:239], v[114:129]
	ds_read_b128 v[194:197], v249 offset:64
	global_load_dwordx4 v[178:181], v227, s[82:83] offset:640
	s_waitcnt lgkmcnt(6)
	v_mfma_f32_32x32x16_bf16 v[130:145], v[206:209], v[236:239], v[130:145]
	ds_read_b128 v[232:235], v248 offset:64
	s_waitcnt vmcnt(15)
	ds_write_b128 v250, v[150:153] offset:46080
	s_waitcnt lgkmcnt(7)
	v_mfma_f32_32x32x16_bf16 v[82:97], v[202:205], v[210:213], v[82:97]
	ds_read_b128 v[198:201], v249 offset:4672
	v_mfma_f32_32x32x16_bf16 v[98:113], v[206:209], v[210:213], v[98:113]
	ds_read_b128 v[236:239], v248 offset:4672
	global_load_dwordx4 v[150:153], v227, s[76:77] offset:640
	s_waitcnt lgkmcnt(7)
	v_mfma_f32_32x32x16_bf16 v[50:65], v[202:205], v[214:217], v[50:65]
	ds_read_b128 v[210:213], v248 offset:9280
	s_waitcnt vmcnt(15)
	ds_write_b128 v251, v[182:185] offset:46080
	v_mfma_f32_32x32x16_bf16 v[66:81], v[206:209], v[214:217], v[66:81]
	s_waitcnt lgkmcnt(8)
	v_mfma_f32_32x32x16_bf16 v[18:33], v[202:205], v[228:231], v[18:33]
	ds_read_b128 v[214:217], v248 offset:13888
	global_load_dwordx4 v[182:185], v227, s[84:85] offset:640
	v_mfma_f32_32x32x16_bf16 v[34:49], v[206:209], v[228:231], v[34:49]
	s_waitcnt vmcnt(15)
	ds_write_b128 v250, v[154:157] offset:55296
	s_waitcnt lgkmcnt(7)
;     ...
;   for (int kt = 0; kt < nk; ++kt) {
;     __syncthreads();
;     if (kt + 1 < nk) {
;       u16* aw = As0 + ((kt + 1) & 1) * 256 * LD;
;       u16* bw = Bs0 + ((kt + 1) & 1) * 256 * LD;
; #pragma unroll
;       for (int i = 0; i < 4; ++i) { *(u32x4*)(aw + (srow + 64 * i) * LD + skc * 8) = ra[i]; *(u32x4*)(bw + (srow + 64 * i) * LD + skc * 8) = rb[i]; }
;     }
;     if (kt + 2 < nk) {
; #pragma unroll
;       for (int i = 0; i < 4; ++i) { ra[i] = *(const u32x4*)(Ag + (size_t)(64 * i) * K + (kt + 2) * 64); rb[i] = *(const u32x4*)(Bg[i] + (kt + 2) * 64); }
;     }
;     __builtin_amdgcn_sched_barrier(0);
;     const u16* as = As0 + (kt & 1) * 256 * LD + (wr * 128 + l31) * LD + h * 8;
;     const u16* bs = Bs0 + (kt & 1) * 256 * LD + (wc * 64 + l31) * LD + h * 8;
;     if (domma)
; #pragma unroll
;     for (int ks = 0; ks < 4; ++ks) {
;       bf16x8 wf[2], xf[4];
; #pragma unroll
;       for (int ct = 0; ct < 2; ++ct) wf[ct] = *(const bf16x8*)(bs + ct * 32 * LD + ks * 16);
; #pragma unroll
;       for (int tt = 0; tt < 4; ++tt) xf[tt] = *(const bf16x8*)(as + tt * 32 * LD + ks * 16);
; #pragma unroll
;       for (int ct = 0; ct < 2; ++ct)
; #pragma unroll
;         for (int tt = 0; tt < 4; ++tt) acc[ct][tt] = __builtin_amdgcn_mfma_f32_32x32x16_bf16(wf[ct], xf[tt], acc[ct][tt], 0, 0, 0);
;     }
;     __builtin_amdgcn_sched_barrier(0);
;   }
	v_mfma_f32_32x32x16_bf16 v[114:129], v[194:197], v[232:235], v[114:129]
	ds_read_b128 v[202:205], v249 offset:96
	s_waitcnt lgkmcnt(6)
	v_mfma_f32_32x32x16_bf16 v[130:145], v[198:201], v[232:235], v[130:145]
	ds_read_b128 v[228:231], v248 offset:96
	global_load_dwordx4 v[154:157], v227, s[78:79] offset:640
	s_waitcnt lgkmcnt(6)
	v_mfma_f32_32x32x16_bf16 v[82:97], v[194:197], v[236:239], v[82:97]
	ds_read_b128 v[206:209], v249 offset:4704
	s_waitcnt vmcnt(15)
	ds_write_b128 v251, v[186:189] offset:55296
	v_mfma_f32_32x32x16_bf16 v[98:113], v[198:201], v[236:239], v[98:113]
	ds_read_b128 v[232:235], v248 offset:4704
	s_waitcnt lgkmcnt(8)
	v_mfma_f32_32x32x16_bf16 v[50:65], v[194:197], v[210:213], v[50:65]
	ds_read_b128 v[236:239], v248 offset:9312
	global_load_dwordx4 v[186:189], v227, s[86:87] offset:640
	v_mfma_f32_32x32x16_bf16 v[66:81], v[198:201], v[210:213], v[66:81]
	s_waitcnt vmcnt(15)
	ds_write_b128 v250, v[158:161] offset:64512
	s_waitcnt lgkmcnt(8)
	v_mfma_f32_32x32x16_bf16 v[18:33], v[194:197], v[214:217], v[18:33]
	ds_read_b128 v[210:213], v248 offset:13920
	v_mfma_f32_32x32x16_bf16 v[34:49], v[198:201], v[214:217], v[34:49]
	global_load_dwordx4 v[158:161], v227, s[80:81] offset:640
	s_waitcnt lgkmcnt(6)
	v_mfma_f32_32x32x16_bf16 v[114:129], v[202:205], v[228:231], v[114:129]
	s_waitcnt vmcnt(15)
	ds_write_b128 v251, v[190:193] offset:64512
	s_waitcnt lgkmcnt(6)
	v_mfma_f32_32x32x16_bf16 v[130:145], v[206:209], v[228:231], v[130:145]
	s_waitcnt lgkmcnt(4)
	v_mfma_f32_32x32x16_bf16 v[82:97], v[202:205], v[232:235], v[82:97]
	global_load_dwordx4 v[190:193], v227, s[92:93] offset:640
	v_mfma_f32_32x32x16_bf16 v[98:113], v[206:209], v[232:235], v[98:113]
	s_waitcnt lgkmcnt(3)
	v_mfma_f32_32x32x16_bf16 v[50:65], v[202:205], v[236:239], v[50:65]
	v_mfma_f32_32x32x16_bf16 v[66:81], v[206:209], v[236:239], v[66:81]
	s_waitcnt lgkmcnt(1)
	v_mfma_f32_32x32x16_bf16 v[18:33], v[202:205], v[210:213], v[18:33]
	v_mfma_f32_32x32x16_bf16 v[34:49], v[206:209], v[210:213], v[34:49]
	s_waitcnt lgkmcnt(0)
	s_barrier
	ds_read_b128 v[194:197], v249 offset:36864
	ds_read_b128 v[210:213], v248 offset:36864
	ds_read_b128 v[198:201], v249 offset:41472
	ds_read_b128 v[214:217], v248 offset:41472
	ds_read_b128 v[228:231], v248 offset:46080
	ds_read_b128 v[232:235], v248 offset:50688
	s_waitcnt lgkmcnt(4)
	v_mfma_f32_32x32x16_bf16 v[114:129], v[194:197], v[210:213], v[114:129]
	ds_read_b128 v[202:205], v249 offset:36896
	s_waitcnt lgkmcnt(4)
	v_mfma_f32_32x32x16_bf16 v[130:145], v[198:201], v[210:213], v[130:145]
	ds_read_b128 v[236:239], v248 offset:36896
	s_waitcnt lgkmcnt(4)
	v_mfma_f32_32x32x16_bf16 v[82:97], v[194:197], v[214:217], v[82:97]
	ds_read_b128 v[206:209], v249 offset:41504
	v_mfma_f32_32x32x16_bf16 v[98:113], v[198:201], v[214:217], v[98:113]
	ds_read_b128 v[210:213], v248 offset:41504
	s_waitcnt vmcnt(15)
	ds_write_b128 v250, v[2:5]
	s_waitcnt lgkmcnt(6)
	v_mfma_f32_32x32x16_bf16 v[50:65], v[194:197], v[228:231], v[50:65]
	ds_read_b128 v[214:217], v248 offset:46112
	v_mfma_f32_32x32x16_bf16 v[66:81], v[198:201], v[228:231], v[66:81]
	global_load_dwordx4 v[2:5], v227, s[74:75] offset:768
	s_waitcnt lgkmcnt(6)
	v_mfma_f32_32x32x16_bf16 v[18:33], v[194:197], v[232:235], v[18:33]
	ds_read_b128 v[228:231], v248 offset:50720
	s_waitcnt vmcnt(15)
	ds_write_b128 v251, v[162:165]
	v_mfma_f32_32x32x16_bf16 v[34:49], v[198:201], v[232:235], v[34:49]
	s_waitcnt lgkmcnt(6)
	v_mfma_f32_32x32x16_bf16 v[114:129], v[202:205], v[236:239], v[114:129]
	ds_read_b128 v[194:197], v249 offset:36928
	global_load_dwordx4 v[162:165], v227, s[82:83] offset:768
	s_waitcnt lgkmcnt(6)
	v_mfma_f32_32x32x16_bf16 v[130:145], v[206:209], v[236:239], v[130:145]
	ds_read_b128 v[232:235], v248 offset:36928
	s_waitcnt vmcnt(15)
	ds_write_b128 v250, v[6:9] offset:9216
	s_waitcnt lgkmcnt(7)
	v_mfma_f32_32x32x16_bf16 v[82:97], v[202:205], v[210:213], v[82:97]
	ds_read_b128 v[198:201], v249 offset:41536
	v_mfma_f32_32x32x16_bf16 v[98:113], v[206:209], v[210:213], v[98:113]
	ds_read_b128 v[236:239], v248 offset:41536
	global_load_dwordx4 v[6:9], v227, s[76:77] offset:768
	s_waitcnt lgkmcnt(7)
	v_mfma_f32_32x32x16_bf16 v[50:65], v[202:205], v[214:217], v[50:65]
	ds_read_b128 v[210:213], v248 offset:46144
	s_waitcnt vmcnt(15)
	ds_write_b128 v251, v[166:169] offset:9216
	v_mfma_f32_32x32x16_bf16 v[66:81], v[206:209], v[214:217], v[66:81]
	s_waitcnt lgkmcnt(8)
	v_mfma_f32_32x32x16_bf16 v[18:33], v[202:205], v[228:231], v[18:33]
	ds_read_b128 v[214:217], v248 offset:50752
	global_load_dwordx4 v[166:169], v227, s[84:85] offset:768
	v_mfma_f32_32x32x16_bf16 v[34:49], v[206:209], v[228:231], v[34:49]
	s_waitcnt vmcnt(15)
	ds_write_b128 v250, v[10:13] offset:18432
	s_waitcnt lgkmcnt(7)
	v_mfma_f32_32x32x16_bf16 v[114:129], v[194:197], v[232:235], v[114:129]
	ds_read_b128 v[202:205], v249 offset:36960
	s_waitcnt lgkmcnt(6)
	v_mfma_f32_32x32x16_bf16 v[130:145], v[198:201], v[232:235], v[130:145]
	ds_read_b128 v[228:231], v248 offset:36960
	global_load_dwordx4 v[10:13], v227, s[78:79] offset:768
	s_waitcnt lgkmcnt(6)
	v_mfma_f32_32x32x16_bf16 v[82:97], v[194:197], v[236:239], v[82:97]
	ds_read_b128 v[206:209], v249 offset:41568
	s_waitcnt vmcnt(15)
	ds_write_b128 v251, v[170:173] offset:18432
	v_mfma_f32_32x32x16_bf16 v[98:113], v[198:201], v[236:239], v[98:113]
	ds_read_b128 v[232:235], v248 offset:41568
	s_waitcnt lgkmcnt(8)
	v_mfma_f32_32x32x16_bf16 v[50:65], v[194:197], v[210:213], v[50:65]
	ds_read_b128 v[236:239], v248 offset:46176
	global_load_dwordx4 v[170:173], v227, s[86:87] offset:768
	v_mfma_f32_32x32x16_bf16 v[66:81], v[198:201], v[210:213], v[66:81]
	s_waitcnt vmcnt(15)
	ds_write_b128 v250, v[14:17] offset:27648
	s_waitcnt lgkmcnt(8)
	v_mfma_f32_32x32x16_bf16 v[18:33], v[194:197], v[214:217], v[18:33]
	ds_read_b128 v[210:213], v248 offset:50784
	v_mfma_f32_32x32x16_bf16 v[34:49], v[198:201], v[214:217], v[34:49]
	global_load_dwordx4 v[14:17], v227, s[80:81] offset:768
	s_waitcnt lgkmcnt(6)
	v_mfma_f32_32x32x16_bf16 v[114:129], v[202:205], v[228:231], v[114:129]
	s_waitcnt vmcnt(15)
	ds_write_b128 v251, v[174:177] offset:27648
	s_waitcnt lgkmcnt(6)
	v_mfma_f32_32x32x16_bf16 v[130:145], v[206:209], v[228:231], v[130:145]
	s_waitcnt lgkmcnt(4)
	v_mfma_f32_32x32x16_bf16 v[82:97], v[202:205], v[232:235], v[82:97]
	global_load_dwordx4 v[174:177], v227, s[92:93] offset:768
	v_mfma_f32_32x32x16_bf16 v[98:113], v[206:209], v[232:235], v[98:113]
	s_waitcnt lgkmcnt(3)
	v_mfma_f32_32x32x16_bf16 v[50:65], v[202:205], v[236:239], v[50:65]
	v_mfma_f32_32x32x16_bf16 v[66:81], v[206:209], v[236:239], v[66:81]
	s_waitcnt lgkmcnt(1)
	v_mfma_f32_32x32x16_bf16 v[18:33], v[202:205], v[210:213], v[18:33]
	v_mfma_f32_32x32x16_bf16 v[34:49], v[206:209], v[210:213], v[34:49]
	s_waitcnt lgkmcnt(0)
	s_barrier
;     ...
;   for (int kt = 0; kt < nk; ++kt) {
;     __syncthreads();
;     if (kt + 1 < nk) {
;       u16* aw = As0 + ((kt + 1) & 1) * 256 * LD;
;       u16* bw = Bs0 + ((kt + 1) & 1) * 256 * LD;
; #pragma unroll
;       for (int i = 0; i < 4; ++i) { *(u32x4*)(aw + (srow + 64 * i) * LD + skc * 8) = ra[i]; *(u32x4*)(bw + (srow + 64 * i) * LD + skc * 8) = rb[i]; }
;     }
;     if (kt + 2 < nk) {
; #pragma unroll
;       for (int i = 0; i < 4; ++i) { ra[i] = *(const u32x4*)(Ag + (size_t)(64 * i) * K + (kt + 2) * 64); rb[i] = *(const u32x4*)(Bg[i] + (kt + 2) * 64); }
;     }
;     __builtin_amdgcn_sched_barrier(0);
;     const u16* as = As0 + (kt & 1) * 256 * LD + (wr * 128 + l31) * LD + h * 8;
;     const u16* bs = Bs0 + (kt & 1) * 256 * LD + (wc * 64 + l31) * LD + h * 8;
;     if (domma)
; #pragma unroll
;     for (int ks = 0; ks < 4; ++ks) {
;       bf16x8 wf[2], xf[4];
; #pragma unroll
;       for (int ct = 0; ct < 2; ++ct) wf[ct] = *(const bf16x8*)(bs + ct * 32 * LD + ks * 16);
; #pragma unroll
;       for (int tt = 0; tt < 4; ++tt) xf[tt] = *(const bf16x8*)(as + tt * 32 * LD + ks * 16);
; #pragma unroll
;       for (int ct = 0; ct < 2; ++ct)
; #pragma unroll
;         for (int tt = 0; tt < 4; ++tt) acc[ct][tt] = __builtin_amdgcn_mfma_f32_32x32x16_bf16(wf[ct], xf[tt], acc[ct][tt], 0, 0, 0);
;     }
;     __builtin_amdgcn_sched_barrier(0);
;   }
	ds_read_b128 v[194:197], v249
	ds_read_b128 v[210:213], v248
	ds_read_b128 v[198:201], v249 offset:4608
	ds_read_b128 v[214:217], v248 offset:4608
	ds_read_b128 v[228:231], v248 offset:9216
	ds_read_b128 v[232:235], v248 offset:13824
	s_waitcnt lgkmcnt(4)
	v_mfma_f32_32x32x16_bf16 v[114:129], v[194:197], v[210:213], v[114:129]
	ds_read_b128 v[202:205], v249 offset:32
	s_waitcnt lgkmcnt(4)
	v_mfma_f32_32x32x16_bf16 v[130:145], v[198:201], v[210:213], v[130:145]
	ds_read_b128 v[236:239], v248 offset:32
	s_waitcnt lgkmcnt(4)
	v_mfma_f32_32x32x16_bf16 v[82:97], v[194:197], v[214:217], v[82:97]
	ds_read_b128 v[206:209], v249 offset:4640
	v_mfma_f32_32x32x16_bf16 v[98:113], v[198:201], v[214:217], v[98:113]
	ds_read_b128 v[210:213], v248 offset:4640
	s_waitcnt vmcnt(15)
	ds_write_b128 v250, v[146:149] offset:36864
	s_waitcnt lgkmcnt(6)
	v_mfma_f32_32x32x16_bf16 v[50:65], v[194:197], v[228:231], v[50:65]
	ds_read_b128 v[214:217], v248 offset:9248
	v_mfma_f32_32x32x16_bf16 v[66:81], v[198:201], v[228:231], v[66:81]
	global_load_dwordx4 v[146:149], v227, s[74:75] offset:896
	s_waitcnt lgkmcnt(6)
	v_mfma_f32_32x32x16_bf16 v[18:33], v[194:197], v[232:235], v[18:33]
	ds_read_b128 v[228:231], v248 offset:13856
	s_waitcnt vmcnt(15)
	ds_write_b128 v251, v[178:181] offset:36864
	v_mfma_f32_32x32x16_bf16 v[34:49], v[198:201], v[232:235], v[34:49]
	s_waitcnt lgkmcnt(6)
	v_mfma_f32_32x32x16_bf16 v[114:129], v[202:205], v[236:239], v[114:129]
	ds_read_b128 v[194:197], v249 offset:64
	global_load_dwordx4 v[178:181], v227, s[82:83] offset:896
	s_waitcnt lgkmcnt(6)
	v_mfma_f32_32x32x16_bf16 v[130:145], v[206:209], v[236:239], v[130:145]
	ds_read_b128 v[232:235], v248 offset:64
	s_waitcnt vmcnt(15)
	ds_write_b128 v250, v[150:153] offset:46080
	s_waitcnt lgkmcnt(7)
	v_mfma_f32_32x32x16_bf16 v[82:97], v[202:205], v[210:213], v[82:97]
	ds_read_b128 v[198:201], v249 offset:4672
	v_mfma_f32_32x32x16_bf16 v[98:113], v[206:209], v[210:213], v[98:113]
	ds_read_b128 v[236:239], v248 offset:4672
	global_load_dwordx4 v[150:153], v227, s[76:77] offset:896
	s_waitcnt lgkmcnt(7)
	v_mfma_f32_32x32x16_bf16 v[50:65], v[202:205], v[214:217], v[50:65]
	ds_read_b128 v[210:213], v248 offset:9280
	s_waitcnt vmcnt(15)
	ds_write_b128 v251, v[182:185] offset:46080
	v_mfma_f32_32x32x16_bf16 v[66:81], v[206:209], v[214:217], v[66:81]
	s_waitcnt lgkmcnt(8)
	v_mfma_f32_32x32x16_bf16 v[18:33], v[202:205], v[228:231], v[18:33]
	ds_read_b128 v[214:217], v248 offset:13888
	global_load_dwordx4 v[182:185], v227, s[84:85] offset:896
	v_mfma_f32_32x32x16_bf16 v[34:49], v[206:209], v[228:231], v[34:49]
	s_waitcnt vmcnt(15)
	ds_write_b128 v250, v[154:157] offset:55296
	s_waitcnt lgkmcnt(7)
	v_mfma_f32_32x32x16_bf16 v[114:129], v[194:197], v[232:235], v[114:129]
	ds_read_b128 v[202:205], v249 offset:96
	s_waitcnt lgkmcnt(6)
	v_mfma_f32_32x32x16_bf16 v[130:145], v[198:201], v[232:235], v[130:145]
	ds_read_b128 v[228:231], v248 offset:96
	global_load_dwordx4 v[154:157], v227, s[78:79] offset:896
	s_waitcnt lgkmcnt(6)
	v_mfma_f32_32x32x16_bf16 v[82:97], v[194:197], v[236:239], v[82:97]
	ds_read_b128 v[206:209], v249 offset:4704
	s_waitcnt vmcnt(15)
	ds_write_b128 v251, v[186:189] offset:55296
	v_mfma_f32_32x32x16_bf16 v[98:113], v[198:201], v[236:239], v[98:113]
	ds_read_b128 v[232:235], v248 offset:4704
	s_waitcnt lgkmcnt(8)
	v_mfma_f32_32x32x16_bf16 v[50:65], v[194:197], v[210:213], v[50:65]
	ds_read_b128 v[236:239], v248 offset:9312
	global_load_dwordx4 v[186:189], v227, s[86:87] offset:896
	v_mfma_f32_32x32x16_bf16 v[66:81], v[198:201], v[210:213], v[66:81]
	s_waitcnt vmcnt(15)
	ds_write_b128 v250, v[158:161] offset:64512
	s_waitcnt lgkmcnt(8)
	v_mfma_f32_32x32x16_bf16 v[18:33], v[194:197], v[214:217], v[18:33]
	ds_read_b128 v[210:213], v248 offset:13920
	v_mfma_f32_32x32x16_bf16 v[34:49], v[198:201], v[214:217], v[34:49]
	global_load_dwordx4 v[158:161], v227, s[80:81] offset:896
	s_waitcnt lgkmcnt(6)
	v_mfma_f32_32x32x16_bf16 v[114:129], v[202:205], v[228:231], v[114:129]
	s_waitcnt vmcnt(15)
	ds_write_b128 v251, v[190:193] offset:64512
	s_waitcnt lgkmcnt(6)
	v_mfma_f32_32x32x16_bf16 v[130:145], v[206:209], v[228:231], v[130:145]
	s_waitcnt lgkmcnt(4)
	v_mfma_f32_32x32x16_bf16 v[82:97], v[202:205], v[232:235], v[82:97]
	global_load_dwordx4 v[190:193], v227, s[92:93] offset:896
	v_mfma_f32_32x32x16_bf16 v[98:113], v[206:209], v[232:235], v[98:113]
	s_waitcnt lgkmcnt(3)
	v_mfma_f32_32x32x16_bf16 v[50:65], v[202:205], v[236:239], v[50:65]
	v_mfma_f32_32x32x16_bf16 v[66:81], v[206:209], v[236:239], v[66:81]
	s_waitcnt lgkmcnt(1)
	v_mfma_f32_32x32x16_bf16 v[18:33], v[202:205], v[210:213], v[18:33]
	v_mfma_f32_32x32x16_bf16 v[34:49], v[206:209], v[210:213], v[34:49]
	s_waitcnt lgkmcnt(0)
	s_barrier
;     ...
;   for (int kt = 0; kt < nk; ++kt) {
;     __syncthreads();
;     if (kt + 1 < nk) {
;       u16* aw = As0 + ((kt + 1) & 1) * 256 * LD;
;       u16* bw = Bs0 + ((kt + 1) & 1) * 256 * LD;
; #pragma unroll
;       for (int i = 0; i < 4; ++i) { *(u32x4*)(aw + (srow + 64 * i) * LD + skc * 8) = ra[i]; *(u32x4*)(bw + (srow + 64 * i) * LD + skc * 8) = rb[i]; }
;     }
;     if (kt + 2 < nk) {
; #pragma unroll
;       for (int i = 0; i < 4; ++i) { ra[i] = *(const u32x4*)(Ag + (size_t)(64 * i) * K + (kt + 2) * 64); rb[i] = *(const u32x4*)(Bg[i] + (kt + 2) * 64); }
;     }
;     __builtin_amdgcn_sched_barrier(0);
;     const u16* as = As0 + (kt & 1) * 256 * LD + (wr * 128 + l31) * LD + h * 8;
;     const u16* bs = Bs0 + (kt & 1) * 256 * LD + (wc * 64 + l31) * LD + h * 8;
;     if (domma)
; #pragma unroll
;     for (int ks = 0; ks < 4; ++ks) {
;       bf16x8 wf[2], xf[4];
; #pragma unroll
;       for (int ct = 0; ct < 2; ++ct) wf[ct] = *(const bf16x8*)(bs + ct * 32 * LD + ks * 16);
; #pragma unroll
;       for (int tt = 0; tt < 4; ++tt) xf[tt] = *(const bf16x8*)(as + tt * 32 * LD + ks * 16);
; #pragma unroll
;       for (int ct = 0; ct < 2; ++ct)
; #pragma unroll
;         for (int tt = 0; tt < 4; ++tt) acc[ct][tt] = __builtin_amdgcn_mfma_f32_32x32x16_bf16(wf[ct], xf[tt], acc[ct][tt], 0, 0, 0);
;     }
;     __builtin_amdgcn_sched_barrier(0);
;   }
	ds_read_b128 v[194:197], v249 offset:36864
	ds_read_b128 v[210:213], v248 offset:36864
	ds_read_b128 v[198:201], v249 offset:41472
	ds_read_b128 v[214:217], v248 offset:41472
	ds_read_b128 v[228:231], v248 offset:46080
	ds_read_b128 v[232:235], v248 offset:50688
	s_waitcnt lgkmcnt(4)
	v_mfma_f32_32x32x16_bf16 v[114:129], v[194:197], v[210:213], v[114:129]
	ds_read_b128 v[202:205], v249 offset:36896
	s_waitcnt lgkmcnt(4)
	v_mfma_f32_32x32x16_bf16 v[130:145], v[198:201], v[210:213], v[130:145]
	ds_read_b128 v[236:239], v248 offset:36896
	s_waitcnt lgkmcnt(4)
	v_mfma_f32_32x32x16_bf16 v[82:97], v[194:197], v[214:217], v[82:97]
	ds_read_b128 v[206:209], v249 offset:41504
	v_mfma_f32_32x32x16_bf16 v[98:113], v[198:201], v[214:217], v[98:113]
	ds_read_b128 v[210:213], v248 offset:41504
	s_waitcnt vmcnt(15)
	ds_write_b128 v250, v[2:5]
	s_waitcnt lgkmcnt(6)
	v_mfma_f32_32x32x16_bf16 v[50:65], v[194:197], v[228:231], v[50:65]
	ds_read_b128 v[214:217], v248 offset:46112
	v_mfma_f32_32x32x16_bf16 v[66:81], v[198:201], v[228:231], v[66:81]
	global_load_dwordx4 v[2:5], v227, s[74:75] offset:1024
	s_waitcnt lgkmcnt(6)
	v_mfma_f32_32x32x16_bf16 v[18:33], v[194:197], v[232:235], v[18:33]
	ds_read_b128 v[228:231], v248 offset:50720
	s_waitcnt vmcnt(15)
	ds_write_b128 v251, v[162:165]
	v_mfma_f32_32x32x16_bf16 v[34:49], v[198:201], v[232:235], v[34:49]
	s_waitcnt lgkmcnt(6)
	v_mfma_f32_32x32x16_bf16 v[114:129], v[202:205], v[236:239], v[114:129]
	ds_read_b128 v[194:197], v249 offset:36928
	global_load_dwordx4 v[162:165], v227, s[82:83] offset:1024
	s_waitcnt lgkmcnt(6)
	v_mfma_f32_32x32x16_bf16 v[130:145], v[206:209], v[236:239], v[130:145]
	ds_read_b128 v[232:235], v248 offset:36928
	s_waitcnt vmcnt(15)
	ds_write_b128 v250, v[6:9] offset:9216
	s_waitcnt lgkmcnt(7)
	v_mfma_f32_32x32x16_bf16 v[82:97], v[202:205], v[210:213], v[82:97]
	ds_read_b128 v[198:201], v249 offset:41536
	v_mfma_f32_32x32x16_bf16 v[98:113], v[206:209], v[210:213], v[98:113]
	ds_read_b128 v[236:239], v248 offset:41536
	global_load_dwordx4 v[6:9], v227, s[76:77] offset:1024
	s_waitcnt lgkmcnt(7)
	v_mfma_f32_32x32x16_bf16 v[50:65], v[202:205], v[214:217], v[50:65]
	ds_read_b128 v[210:213], v248 offset:46144
	s_waitcnt vmcnt(15)
	ds_write_b128 v251, v[166:169] offset:9216
	v_mfma_f32_32x32x16_bf16 v[66:81], v[206:209], v[214:217], v[66:81]
	s_waitcnt lgkmcnt(8)
	v_mfma_f32_32x32x16_bf16 v[18:33], v[202:205], v[228:231], v[18:33]
	ds_read_b128 v[214:217], v248 offset:50752
	global_load_dwordx4 v[166:169], v227, s[84:85] offset:1024
	v_mfma_f32_32x32x16_bf16 v[34:49], v[206:209], v[228:231], v[34:49]
	s_waitcnt vmcnt(15)
	ds_write_b128 v250, v[10:13] offset:18432
	s_waitcnt lgkmcnt(7)
	v_mfma_f32_32x32x16_bf16 v[114:129], v[194:197], v[232:235], v[114:129]
	ds_read_b128 v[202:205], v249 offset:36960
	s_waitcnt lgkmcnt(6)
	v_mfma_f32_32x32x16_bf16 v[130:145], v[198:201], v[232:235], v[130:145]
	ds_read_b128 v[228:231], v248 offset:36960
	global_load_dwordx4 v[10:13], v227, s[78:79] offset:1024
	s_waitcnt lgkmcnt(6)
	v_mfma_f32_32x32x16_bf16 v[82:97], v[194:197], v[236:239], v[82:97]
	ds_read_b128 v[206:209], v249 offset:41568
	s_waitcnt vmcnt(15)
	ds_write_b128 v251, v[170:173] offset:18432
	v_mfma_f32_32x32x16_bf16 v[98:113], v[198:201], v[236:239], v[98:113]
	ds_read_b128 v[232:235], v248 offset:41568
	s_waitcnt lgkmcnt(8)
	v_mfma_f32_32x32x16_bf16 v[50:65], v[194:197], v[210:213], v[50:65]
	ds_read_b128 v[236:239], v248 offset:46176
	global_load_dwordx4 v[170:173], v227, s[86:87] offset:1024
	v_mfma_f32_32x32x16_bf16 v[66:81], v[198:201], v[210:213], v[66:81]
	s_waitcnt vmcnt(15)
	ds_write_b128 v250, v[14:17] offset:27648
	s_waitcnt lgkmcnt(8)
	v_mfma_f32_32x32x16_bf16 v[18:33], v[194:197], v[214:217], v[18:33]
	ds_read_b128 v[210:213], v248 offset:50784
	v_mfma_f32_32x32x16_bf16 v[34:49], v[198:201], v[214:217], v[34:49]
	global_load_dwordx4 v[14:17], v227, s[80:81] offset:1024
	s_waitcnt lgkmcnt(6)
	v_mfma_f32_32x32x16_bf16 v[114:129], v[202:205], v[228:231], v[114:129]
	s_waitcnt vmcnt(15)
	ds_write_b128 v251, v[174:177] offset:27648
	s_waitcnt lgkmcnt(6)
	v_mfma_f32_32x32x16_bf16 v[130:145], v[206:209], v[228:231], v[130:145]
	s_waitcnt lgkmcnt(4)
	v_mfma_f32_32x32x16_bf16 v[82:97], v[202:205], v[232:235], v[82:97]
	global_load_dwordx4 v[174:177], v227, s[92:93] offset:1024
	v_mfma_f32_32x32x16_bf16 v[98:113], v[206:209], v[232:235], v[98:113]
	s_waitcnt lgkmcnt(3)
	v_mfma_f32_32x32x16_bf16 v[50:65], v[202:205], v[236:239], v[50:65]
	v_mfma_f32_32x32x16_bf16 v[66:81], v[206:209], v[236:239], v[66:81]
	s_waitcnt lgkmcnt(1)
	v_mfma_f32_32x32x16_bf16 v[18:33], v[202:205], v[210:213], v[18:33]
	v_mfma_f32_32x32x16_bf16 v[34:49], v[206:209], v[210:213], v[34:49]
	s_waitcnt lgkmcnt(0)
	s_barrier
;     ...
;   for (int kt = 0; kt < nk; ++kt) {
;     __syncthreads();
;     if (kt + 1 < nk) {
;       u16* aw = As0 + ((kt + 1) & 1) * 256 * LD;
;       u16* bw = Bs0 + ((kt + 1) & 1) * 256 * LD;
; #pragma unroll
;       for (int i = 0; i < 4; ++i) { *(u32x4*)(aw + (srow + 64 * i) * LD + skc * 8) = ra[i]; *(u32x4*)(bw + (srow + 64 * i) * LD + skc * 8) = rb[i]; }
;     }
;     if (kt + 2 < nk) {
; #pragma unroll
;       for (int i = 0; i < 4; ++i) { ra[i] = *(const u32x4*)(Ag + (size_t)(64 * i) * K + (kt + 2) * 64); rb[i] = *(const u32x4*)(Bg[i] + (kt + 2) * 64); }
;     }
;     __builtin_amdgcn_sched_barrier(0);
;     const u16* as = As0 + (kt & 1) * 256 * LD + (wr * 128 + l31) * LD + h * 8;
;     const u16* bs = Bs0 + (kt & 1) * 256 * LD + (wc * 64 + l31) * LD + h * 8;
;     if (domma)
; #pragma unroll
;     for (int ks = 0; ks < 4; ++ks) {
;       bf16x8 wf[2], xf[4];
; #pragma unroll
;       for (int ct = 0; ct < 2; ++ct) wf[ct] = *(const bf16x8*)(bs + ct * 32 * LD + ks * 16);
; #pragma unroll
;       for (int tt = 0; tt < 4; ++tt) xf[tt] = *(const bf16x8*)(as + tt * 32 * LD + ks * 16);
; #pragma unroll
;       for (int ct = 0; ct < 2; ++ct)
; #pragma unroll
;         for (int tt = 0; tt < 4; ++tt) acc[ct][tt] = __builtin_amdgcn_mfma_f32_32x32x16_bf16(wf[ct], xf[tt], acc[ct][tt], 0, 0, 0);
;     }
;     __builtin_amdgcn_sched_barrier(0);
;   }
	ds_read_b128 v[194:197], v249
	ds_read_b128 v[210:213], v248
	ds_read_b128 v[198:201], v249 offset:4608
	ds_read_b128 v[214:217], v248 offset:4608
	ds_read_b128 v[228:231], v248 offset:9216
	ds_read_b128 v[232:235], v248 offset:13824
	s_waitcnt lgkmcnt(4)
	v_mfma_f32_32x32x16_bf16 v[114:129], v[194:197], v[210:213], v[114:129]
	ds_read_b128 v[202:205], v249 offset:32
	s_waitcnt lgkmcnt(4)
	v_mfma_f32_32x32x16_bf16 v[130:145], v[198:201], v[210:213], v[130:145]
	ds_read_b128 v[236:239], v248 offset:32
	s_waitcnt lgkmcnt(4)
	v_mfma_f32_32x32x16_bf16 v[82:97], v[194:197], v[214:217], v[82:97]
	ds_read_b128 v[206:209], v249 offset:4640
	v_mfma_f32_32x32x16_bf16 v[98:113], v[198:201], v[214:217], v[98:113]
	ds_read_b128 v[210:213], v248 offset:4640
	s_waitcnt vmcnt(15)
	ds_write_b128 v250, v[146:149] offset:36864
	s_waitcnt lgkmcnt(6)
	v_mfma_f32_32x32x16_bf16 v[50:65], v[194:197], v[228:231], v[50:65]
	ds_read_b128 v[214:217], v248 offset:9248
	v_mfma_f32_32x32x16_bf16 v[66:81], v[198:201], v[228:231], v[66:81]
	global_load_dwordx4 v[146:149], v227, s[74:75] offset:1152
	s_waitcnt lgkmcnt(6)
	v_mfma_f32_32x32x16_bf16 v[18:33], v[194:197], v[232:235], v[18:33]
	ds_read_b128 v[228:231], v248 offset:13856
	s_waitcnt vmcnt(15)
	ds_write_b128 v251, v[178:181] offset:36864
	v_mfma_f32_32x32x16_bf16 v[34:49], v[198:201], v[232:235], v[34:49]
	s_waitcnt lgkmcnt(6)
	v_mfma_f32_32x32x16_bf16 v[114:129], v[202:205], v[236:239], v[114:129]
	ds_read_b128 v[194:197], v249 offset:64
	global_load_dwordx4 v[178:181], v227, s[82:83] offset:1152
	s_waitcnt lgkmcnt(6)
	v_mfma_f32_32x32x16_bf16 v[130:145], v[206:209], v[236:239], v[130:145]
	ds_read_b128 v[232:235], v248 offset:64
	s_waitcnt vmcnt(15)
	ds_write_b128 v250, v[150:153] offset:46080
	s_waitcnt lgkmcnt(7)
	v_mfma_f32_32x32x16_bf16 v[82:97], v[202:205], v[210:213], v[82:97]
	ds_read_b128 v[198:201], v249 offset:4672
	v_mfma_f32_32x32x16_bf16 v[98:113], v[206:209], v[210:213], v[98:113]
	ds_read_b128 v[236:239], v248 offset:4672
	global_load_dwordx4 v[150:153], v227, s[76:77] offset:1152
	s_waitcnt lgkmcnt(7)
	v_mfma_f32_32x32x16_bf16 v[50:65], v[202:205], v[214:217], v[50:65]
	ds_read_b128 v[210:213], v248 offset:9280
	s_waitcnt vmcnt(15)
	ds_write_b128 v251, v[182:185] offset:46080
	v_mfma_f32_32x32x16_bf16 v[66:81], v[206:209], v[214:217], v[66:81]
	s_waitcnt lgkmcnt(8)
	v_mfma_f32_32x32x16_bf16 v[18:33], v[202:205], v[228:231], v[18:33]
	ds_read_b128 v[214:217], v248 offset:13888
	global_load_dwordx4 v[182:185], v227, s[84:85] offset:1152
	v_mfma_f32_32x32x16_bf16 v[34:49], v[206:209], v[228:231], v[34:49]
	s_waitcnt vmcnt(15)
	ds_write_b128 v250, v[154:157] offset:55296
	s_waitcnt lgkmcnt(7)
	v_mfma_f32_32x32x16_bf16 v[114:129], v[194:197], v[232:235], v[114:129]
	ds_read_b128 v[202:205], v249 offset:96
	s_waitcnt lgkmcnt(6)
	v_mfma_f32_32x32x16_bf16 v[130:145], v[198:201], v[232:235], v[130:145]
	ds_read_b128 v[228:231], v248 offset:96
	global_load_dwordx4 v[154:157], v227, s[78:79] offset:1152
	s_waitcnt lgkmcnt(6)
	v_mfma_f32_32x32x16_bf16 v[82:97], v[194:197], v[236:239], v[82:97]
	ds_read_b128 v[206:209], v249 offset:4704
	s_waitcnt vmcnt(15)
	ds_write_b128 v251, v[186:189] offset:55296
	v_mfma_f32_32x32x16_bf16 v[98:113], v[198:201], v[236:239], v[98:113]
	ds_read_b128 v[232:235], v248 offset:4704
	s_waitcnt lgkmcnt(8)
	v_mfma_f32_32x32x16_bf16 v[50:65], v[194:197], v[210:213], v[50:65]
	ds_read_b128 v[236:239], v248 offset:9312
	global_load_dwordx4 v[186:189], v227, s[86:87] offset:1152
	v_mfma_f32_32x32x16_bf16 v[66:81], v[198:201], v[210:213], v[66:81]
	s_waitcnt vmcnt(15)
	ds_write_b128 v250, v[158:161] offset:64512
	s_waitcnt lgkmcnt(8)
	v_mfma_f32_32x32x16_bf16 v[18:33], v[194:197], v[214:217], v[18:33]
	ds_read_b128 v[210:213], v248 offset:13920
	v_mfma_f32_32x32x16_bf16 v[34:49], v[198:201], v[214:217], v[34:49]
	global_load_dwordx4 v[158:161], v227, s[80:81] offset:1152
	s_waitcnt lgkmcnt(6)
	v_mfma_f32_32x32x16_bf16 v[114:129], v[202:205], v[228:231], v[114:129]
	s_waitcnt vmcnt(15)
	ds_write_b128 v251, v[190:193] offset:64512
	s_waitcnt lgkmcnt(6)
	v_mfma_f32_32x32x16_bf16 v[130:145], v[206:209], v[228:231], v[130:145]
	s_waitcnt lgkmcnt(4)
	v_mfma_f32_32x32x16_bf16 v[82:97], v[202:205], v[232:235], v[82:97]
	global_load_dwordx4 v[190:193], v227, s[92:93] offset:1152
	v_mfma_f32_32x32x16_bf16 v[98:113], v[206:209], v[232:235], v[98:113]
	s_waitcnt lgkmcnt(3)
	v_mfma_f32_32x32x16_bf16 v[50:65], v[202:205], v[236:239], v[50:65]
	v_mfma_f32_32x32x16_bf16 v[66:81], v[206:209], v[236:239], v[66:81]
	s_waitcnt lgkmcnt(1)
	v_mfma_f32_32x32x16_bf16 v[18:33], v[202:205], v[210:213], v[18:33]
	v_mfma_f32_32x32x16_bf16 v[34:49], v[206:209], v[210:213], v[34:49]
	s_waitcnt lgkmcnt(0)
	s_barrier
;     ...
;   for (int kt = 0; kt < nk; ++kt) {
;     __syncthreads();
;     if (kt + 1 < nk) {
;       u16* aw = As0 + ((kt + 1) & 1) * 256 * LD;
;       u16* bw = Bs0 + ((kt + 1) & 1) * 256 * LD;
; #pragma unroll
;       for (int i = 0; i < 4; ++i) { *(u32x4*)(aw + (srow + 64 * i) * LD + skc * 8) = ra[i]; *(u32x4*)(bw + (srow + 64 * i) * LD + skc * 8) = rb[i]; }
;     }
;     if (kt + 2 < nk) {
; #pragma unroll
;       for (int i = 0; i < 4; ++i) { ra[i] = *(const u32x4*)(Ag + (size_t)(64 * i) * K + (kt + 2) * 64); rb[i] = *(const u32x4*)(Bg[i] + (kt + 2) * 64); }
;     }
;     __builtin_amdgcn_sched_barrier(0);
;     const u16* as = As0 + (kt & 1) * 256 * LD + (wr * 128 + l31) * LD + h * 8;
;     const u16* bs = Bs0 + (kt & 1) * 256 * LD + (wc * 64 + l31) * LD + h * 8;
;     if (domma)
; #pragma unroll
;     for (int ks = 0; ks < 4; ++ks) {
;       bf16x8 wf[2], xf[4];
; #pragma unroll
;       for (int ct = 0; ct < 2; ++ct) wf[ct] = *(const bf16x8*)(bs + ct * 32 * LD + ks * 16);
; #pragma unroll
;       for (int tt = 0; tt < 4; ++tt) xf[tt] = *(const bf16x8*)(as + tt * 32 * LD + ks * 16);
; #pragma unroll
;       for (int ct = 0; ct < 2; ++ct)
; #pragma unroll
;         for (int tt = 0; tt < 4; ++tt) acc[ct][tt] = __builtin_amdgcn_mfma_f32_32x32x16_bf16(wf[ct], xf[tt], acc[ct][tt], 0, 0, 0);
;     }
;     __builtin_amdgcn_sched_barrier(0);
;   }
	ds_read_b128 v[194:197], v249 offset:36864
	ds_read_b128 v[210:213], v248 offset:36864
	ds_read_b128 v[198:201], v249 offset:41472
	ds_read_b128 v[214:217], v248 offset:41472
	ds_read_b128 v[228:231], v248 offset:46080
	ds_read_b128 v[232:235], v248 offset:50688
	s_waitcnt lgkmcnt(4)
	v_mfma_f32_32x32x16_bf16 v[114:129], v[194:197], v[210:213], v[114:129]
	ds_read_b128 v[202:205], v249 offset:36896
	s_waitcnt lgkmcnt(4)
	v_mfma_f32_32x32x16_bf16 v[130:145], v[198:201], v[210:213], v[130:145]
	ds_read_b128 v[236:239], v248 offset:36896
	s_waitcnt lgkmcnt(4)
	v_mfma_f32_32x32x16_bf16 v[82:97], v[194:197], v[214:217], v[82:97]
	ds_read_b128 v[206:209], v249 offset:41504
	v_mfma_f32_32x32x16_bf16 v[98:113], v[198:201], v[214:217], v[98:113]
	ds_read_b128 v[210:213], v248 offset:41504
	s_waitcnt vmcnt(15)
	ds_write_b128 v250, v[2:5]
	s_waitcnt lgkmcnt(6)
	v_mfma_f32_32x32x16_bf16 v[50:65], v[194:197], v[228:231], v[50:65]
	ds_read_b128 v[214:217], v248 offset:46112
	v_mfma_f32_32x32x16_bf16 v[66:81], v[198:201], v[228:231], v[66:81]
	global_load_dwordx4 v[2:5], v227, s[74:75] offset:1280
	s_waitcnt lgkmcnt(6)
	v_mfma_f32_32x32x16_bf16 v[18:33], v[194:197], v[232:235], v[18:33]
	ds_read_b128 v[228:231], v248 offset:50720
	s_waitcnt vmcnt(15)
	ds_write_b128 v251, v[162:165]
	v_mfma_f32_32x32x16_bf16 v[34:49], v[198:201], v[232:235], v[34:49]
	s_waitcnt lgkmcnt(6)
	v_mfma_f32_32x32x16_bf16 v[114:129], v[202:205], v[236:239], v[114:129]
	ds_read_b128 v[194:197], v249 offset:36928
	global_load_dwordx4 v[162:165], v227, s[82:83] offset:1280
	s_waitcnt lgkmcnt(6)
	v_mfma_f32_32x32x16_bf16 v[130:145], v[206:209], v[236:239], v[130:145]
	ds_read_b128 v[232:235], v248 offset:36928
	s_waitcnt vmcnt(15)
	ds_write_b128 v250, v[6:9] offset:9216
	s_waitcnt lgkmcnt(7)
	v_mfma_f32_32x32x16_bf16 v[82:97], v[202:205], v[210:213], v[82:97]
	ds_read_b128 v[198:201], v249 offset:41536
	v_mfma_f32_32x32x16_bf16 v[98:113], v[206:209], v[210:213], v[98:113]
	ds_read_b128 v[236:239], v248 offset:41536
	global_load_dwordx4 v[6:9], v227, s[76:77] offset:1280
	s_waitcnt lgkmcnt(7)
	v_mfma_f32_32x32x16_bf16 v[50:65], v[202:205], v[214:217], v[50:65]
	ds_read_b128 v[210:213], v248 offset:46144
	s_waitcnt vmcnt(15)
	ds_write_b128 v251, v[166:169] offset:9216
	v_mfma_f32_32x32x16_bf16 v[66:81], v[206:209], v[214:217], v[66:81]
	s_waitcnt lgkmcnt(8)
	v_mfma_f32_32x32x16_bf16 v[18:33], v[202:205], v[228:231], v[18:33]
	ds_read_b128 v[214:217], v248 offset:50752
	global_load_dwordx4 v[166:169], v227, s[84:85] offset:1280
	v_mfma_f32_32x32x16_bf16 v[34:49], v[206:209], v[228:231], v[34:49]
	s_waitcnt vmcnt(15)
	ds_write_b128 v250, v[10:13] offset:18432
	s_waitcnt lgkmcnt(7)
	v_mfma_f32_32x32x16_bf16 v[114:129], v[194:197], v[232:235], v[114:129]
	ds_read_b128 v[202:205], v249 offset:36960
	s_waitcnt lgkmcnt(6)
	v_mfma_f32_32x32x16_bf16 v[130:145], v[198:201], v[232:235], v[130:145]
	ds_read_b128 v[228:231], v248 offset:36960
	global_load_dwordx4 v[10:13], v227, s[78:79] offset:1280
	s_waitcnt lgkmcnt(6)
	v_mfma_f32_32x32x16_bf16 v[82:97], v[194:197], v[236:239], v[82:97]
	ds_read_b128 v[206:209], v249 offset:41568
	s_waitcnt vmcnt(15)
	ds_write_b128 v251, v[170:173] offset:18432
	v_mfma_f32_32x32x16_bf16 v[98:113], v[198:201], v[236:239], v[98:113]
	ds_read_b128 v[232:235], v248 offset:41568
	s_waitcnt lgkmcnt(8)
	v_mfma_f32_32x32x16_bf16 v[50:65], v[194:197], v[210:213], v[50:65]
	ds_read_b128 v[236:239], v248 offset:46176
	global_load_dwordx4 v[170:173], v227, s[86:87] offset:1280
	v_mfma_f32_32x32x16_bf16 v[66:81], v[198:201], v[210:213], v[66:81]
	s_waitcnt vmcnt(15)
	ds_write_b128 v250, v[14:17] offset:27648
	s_waitcnt lgkmcnt(8)
	v_mfma_f32_32x32x16_bf16 v[18:33], v[194:197], v[214:217], v[18:33]
	ds_read_b128 v[210:213], v248 offset:50784
	v_mfma_f32_32x32x16_bf16 v[34:49], v[198:201], v[214:217], v[34:49]
	global_load_dwordx4 v[14:17], v227, s[80:81] offset:1280
	s_waitcnt lgkmcnt(6)
	v_mfma_f32_32x32x16_bf16 v[114:129], v[202:205], v[228:231], v[114:129]
	s_waitcnt vmcnt(15)
	ds_write_b128 v251, v[174:177] offset:27648
	s_waitcnt lgkmcnt(6)
	v_mfma_f32_32x32x16_bf16 v[130:145], v[206:209], v[228:231], v[130:145]
	s_waitcnt lgkmcnt(4)
	v_mfma_f32_32x32x16_bf16 v[82:97], v[202:205], v[232:235], v[82:97]
	global_load_dwordx4 v[174:177], v227, s[92:93] offset:1280
	v_mfma_f32_32x32x16_bf16 v[98:113], v[206:209], v[232:235], v[98:113]
	s_waitcnt lgkmcnt(3)
	v_mfma_f32_32x32x16_bf16 v[50:65], v[202:205], v[236:239], v[50:65]
	v_mfma_f32_32x32x16_bf16 v[66:81], v[206:209], v[236:239], v[66:81]
	s_waitcnt lgkmcnt(1)
	v_mfma_f32_32x32x16_bf16 v[18:33], v[202:205], v[210:213], v[18:33]
	v_mfma_f32_32x32x16_bf16 v[34:49], v[206:209], v[210:213], v[34:49]
	s_waitcnt lgkmcnt(0)
	s_barrier
;     ...
;   for (int kt = 0; kt < nk; ++kt) {
;     __syncthreads();
;     if (kt + 1 < nk) {
;       u16* aw = As0 + ((kt + 1) & 1) * 256 * LD;
;       u16* bw = Bs0 + ((kt + 1) & 1) * 256 * LD;
; #pragma unroll
;       for (int i = 0; i < 4; ++i) { *(u32x4*)(aw + (srow + 64 * i) * LD + skc * 8) = ra[i]; *(u32x4*)(bw + (srow + 64 * i) * LD + skc * 8) = rb[i]; }
;     }
;     if (kt + 2 < nk) {
; #pragma unroll
;       for (int i = 0; i < 4; ++i) { ra[i] = *(const u32x4*)(Ag + (size_t)(64 * i) * K + (kt + 2) * 64); rb[i] = *(const u32x4*)(Bg[i] + (kt + 2) * 64); }
;     }
;     __builtin_amdgcn_sched_barrier(0);
;     const u16* as = As0 + (kt & 1) * 256 * LD + (wr * 128 + l31) * LD + h * 8;
;     const u16* bs = Bs0 + (kt & 1) * 256 * LD + (wc * 64 + l31) * LD + h * 8;
;     if (domma)
; #pragma unroll
;     for (int ks = 0; ks < 4; ++ks) {
;       bf16x8 wf[2], xf[4];
; #pragma unroll
;       for (int ct = 0; ct < 2; ++ct) wf[ct] = *(const bf16x8*)(bs + ct * 32 * LD + ks * 16);
; #pragma unroll
;       for (int tt = 0; tt < 4; ++tt) xf[tt] = *(const bf16x8*)(as + tt * 32 * LD + ks * 16);
; #pragma unroll
;       for (int ct = 0; ct < 2; ++ct)
; #pragma unroll
;         for (int tt = 0; tt < 4; ++tt) acc[ct][tt] = __builtin_amdgcn_mfma_f32_32x32x16_bf16(wf[ct], xf[tt], acc[ct][tt], 0, 0, 0);
;     }
;     __builtin_amdgcn_sched_barrier(0);
;   }
	ds_read_b128 v[194:197], v249
	ds_read_b128 v[210:213], v248
	ds_read_b128 v[198:201], v249 offset:4608
	ds_read_b128 v[214:217], v248 offset:4608
	ds_read_b128 v[228:231], v248 offset:9216
	ds_read_b128 v[232:235], v248 offset:13824
	s_waitcnt lgkmcnt(4)
	v_mfma_f32_32x32x16_bf16 v[114:129], v[194:197], v[210:213], v[114:129]
	ds_read_b128 v[202:205], v249 offset:32
	s_waitcnt lgkmcnt(4)
	v_mfma_f32_32x32x16_bf16 v[130:145], v[198:201], v[210:213], v[130:145]
	ds_read_b128 v[236:239], v248 offset:32
	s_waitcnt lgkmcnt(4)
	v_mfma_f32_32x32x16_bf16 v[82:97], v[194:197], v[214:217], v[82:97]
	ds_read_b128 v[206:209], v249 offset:4640
	v_mfma_f32_32x32x16_bf16 v[98:113], v[198:201], v[214:217], v[98:113]
	ds_read_b128 v[210:213], v248 offset:4640
	s_waitcnt vmcnt(15)
	ds_write_b128 v250, v[146:149] offset:36864
	s_waitcnt lgkmcnt(6)
	v_mfma_f32_32x32x16_bf16 v[50:65], v[194:197], v[228:231], v[50:65]
	ds_read_b128 v[214:217], v248 offset:9248
	v_mfma_f32_32x32x16_bf16 v[66:81], v[198:201], v[228:231], v[66:81]
	global_load_dwordx4 v[146:149], v227, s[74:75] offset:1408
	s_waitcnt lgkmcnt(6)
	v_mfma_f32_32x32x16_bf16 v[18:33], v[194:197], v[232:235], v[18:33]
	ds_read_b128 v[228:231], v248 offset:13856
	s_waitcnt vmcnt(15)
	ds_write_b128 v251, v[178:181] offset:36864
	v_mfma_f32_32x32x16_bf16 v[34:49], v[198:201], v[232:235], v[34:49]
	s_waitcnt lgkmcnt(6)
	v_mfma_f32_32x32x16_bf16 v[114:129], v[202:205], v[236:239], v[114:129]
	ds_read_b128 v[194:197], v249 offset:64
	global_load_dwordx4 v[178:181], v227, s[82:83] offset:1408
	s_waitcnt lgkmcnt(6)
	v_mfma_f32_32x32x16_bf16 v[130:145], v[206:209], v[236:239], v[130:145]
	ds_read_b128 v[232:235], v248 offset:64
	s_waitcnt vmcnt(15)
	ds_write_b128 v250, v[150:153] offset:46080
	s_waitcnt lgkmcnt(7)
	v_mfma_f32_32x32x16_bf16 v[82:97], v[202:205], v[210:213], v[82:97]
	ds_read_b128 v[198:201], v249 offset:4672
	v_mfma_f32_32x32x16_bf16 v[98:113], v[206:209], v[210:213], v[98:113]
	ds_read_b128 v[236:239], v248 offset:4672
	global_load_dwordx4 v[150:153], v227, s[76:77] offset:1408
	s_waitcnt lgkmcnt(7)
	v_mfma_f32_32x32x16_bf16 v[50:65], v[202:205], v[214:217], v[50:65]
	ds_read_b128 v[210:213], v248 offset:9280
	s_waitcnt vmcnt(15)
	ds_write_b128 v251, v[182:185] offset:46080
	v_mfma_f32_32x32x16_bf16 v[66:81], v[206:209], v[214:217], v[66:81]
	s_waitcnt lgkmcnt(8)
	v_mfma_f32_32x32x16_bf16 v[18:33], v[202:205], v[228:231], v[18:33]
	ds_read_b128 v[214:217], v248 offset:13888
	global_load_dwordx4 v[182:185], v227, s[84:85] offset:1408
	v_mfma_f32_32x32x16_bf16 v[34:49], v[206:209], v[228:231], v[34:49]
	s_waitcnt vmcnt(15)
	ds_write_b128 v250, v[154:157] offset:55296
	s_waitcnt lgkmcnt(7)
	v_mfma_f32_32x32x16_bf16 v[114:129], v[194:197], v[232:235], v[114:129]
	ds_read_b128 v[202:205], v249 offset:96
	s_waitcnt lgkmcnt(6)
	v_mfma_f32_32x32x16_bf16 v[130:145], v[198:201], v[232:235], v[130:145]
	ds_read_b128 v[228:231], v248 offset:96
	global_load_dwordx4 v[154:157], v227, s[78:79] offset:1408
	s_waitcnt lgkmcnt(6)
	v_mfma_f32_32x32x16_bf16 v[82:97], v[194:197], v[236:239], v[82:97]
	ds_read_b128 v[206:209], v249 offset:4704
	s_waitcnt vmcnt(15)
	ds_write_b128 v251, v[186:189] offset:55296
	v_mfma_f32_32x32x16_bf16 v[98:113], v[198:201], v[236:239], v[98:113]
	ds_read_b128 v[232:235], v248 offset:4704
	s_waitcnt lgkmcnt(8)
	v_mfma_f32_32x32x16_bf16 v[50:65], v[194:197], v[210:213], v[50:65]
	ds_read_b128 v[236:239], v248 offset:9312
	global_load_dwordx4 v[186:189], v227, s[86:87] offset:1408
	v_mfma_f32_32x32x16_bf16 v[66:81], v[198:201], v[210:213], v[66:81]
	s_waitcnt vmcnt(15)
	ds_write_b128 v250, v[158:161] offset:64512
	s_waitcnt lgkmcnt(8)
	v_mfma_f32_32x32x16_bf16 v[18:33], v[194:197], v[214:217], v[18:33]
	ds_read_b128 v[210:213], v248 offset:13920
	v_mfma_f32_32x32x16_bf16 v[34:49], v[198:201], v[214:217], v[34:49]
	global_load_dwordx4 v[158:161], v227, s[80:81] offset:1408
	s_waitcnt lgkmcnt(6)
	v_mfma_f32_32x32x16_bf16 v[114:129], v[202:205], v[228:231], v[114:129]
	s_waitcnt vmcnt(15)
	ds_write_b128 v251, v[190:193] offset:64512
	s_waitcnt lgkmcnt(6)
	v_mfma_f32_32x32x16_bf16 v[130:145], v[206:209], v[228:231], v[130:145]
	s_waitcnt lgkmcnt(4)
	v_mfma_f32_32x32x16_bf16 v[82:97], v[202:205], v[232:235], v[82:97]
	global_load_dwordx4 v[190:193], v227, s[92:93] offset:1408
	v_mfma_f32_32x32x16_bf16 v[98:113], v[206:209], v[232:235], v[98:113]
	s_waitcnt lgkmcnt(3)
	v_mfma_f32_32x32x16_bf16 v[50:65], v[202:205], v[236:239], v[50:65]
	v_mfma_f32_32x32x16_bf16 v[66:81], v[206:209], v[236:239], v[66:81]
	s_waitcnt lgkmcnt(1)
	v_mfma_f32_32x32x16_bf16 v[18:33], v[202:205], v[210:213], v[18:33]
	v_mfma_f32_32x32x16_bf16 v[34:49], v[206:209], v[210:213], v[34:49]
	s_waitcnt lgkmcnt(0)
	s_barrier
;     ...
;   for (int kt = 0; kt < nk; ++kt) {
;     __syncthreads();
;     if (kt + 1 < nk) {
;       u16* aw = As0 + ((kt + 1) & 1) * 256 * LD;
;       u16* bw = Bs0 + ((kt + 1) & 1) * 256 * LD;
; #pragma unroll
;       for (int i = 0; i < 4; ++i) { *(u32x4*)(aw + (srow + 64 * i) * LD + skc * 8) = ra[i]; *(u32x4*)(bw + (srow + 64 * i) * LD + skc * 8) = rb[i]; }
;     }
;     if (kt + 2 < nk) {
; #pragma unroll
;       for (int i = 0; i < 4; ++i) { ra[i] = *(const u32x4*)(Ag + (size_t)(64 * i) * K + (kt + 2) * 64); rb[i] = *(const u32x4*)(Bg[i] + (kt + 2) * 64); }
;     }
;     __builtin_amdgcn_sched_barrier(0);
;     const u16* as = As0 + (kt & 1) * 256 * LD + (wr * 128 + l31) * LD + h * 8;
;     const u16* bs = Bs0 + (kt & 1) * 256 * LD + (wc * 64 + l31) * LD + h * 8;
;     if (domma)
; #pragma unroll
;     for (int ks = 0; ks < 4; ++ks) {
;       bf16x8 wf[2], xf[4];
; #pragma unroll
;       for (int ct = 0; ct < 2; ++ct) wf[ct] = *(const bf16x8*)(bs + ct * 32 * LD + ks * 16);
; #pragma unroll
;       for (int tt = 0; tt < 4; ++tt) xf[tt] = *(const bf16x8*)(as + tt * 32 * LD + ks * 16);
; #pragma unroll
;       for (int ct = 0; ct < 2; ++ct)
; #pragma unroll
;         for (int tt = 0; tt < 4; ++tt) acc[ct][tt] = __builtin_amdgcn_mfma_f32_32x32x16_bf16(wf[ct], xf[tt], acc[ct][tt], 0, 0, 0);
;     }
;     __builtin_amdgcn_sched_barrier(0);
;   }
	ds_read_b128 v[194:197], v249 offset:36864
	ds_read_b128 v[210:213], v248 offset:36864
	ds_read_b128 v[198:201], v249 offset:41472
	ds_read_b128 v[214:217], v248 offset:41472
	ds_read_b128 v[228:231], v248 offset:46080
	ds_read_b128 v[232:235], v248 offset:50688
	s_waitcnt lgkmcnt(4)
	v_mfma_f32_32x32x16_bf16 v[114:129], v[194:197], v[210:213], v[114:129]
	ds_read_b128 v[202:205], v249 offset:36896
	s_waitcnt lgkmcnt(4)
	v_mfma_f32_32x32x16_bf16 v[130:145], v[198:201], v[210:213], v[130:145]
	ds_read_b128 v[236:239], v248 offset:36896
	s_waitcnt lgkmcnt(4)
	v_mfma_f32_32x32x16_bf16 v[82:97], v[194:197], v[214:217], v[82:97]
	ds_read_b128 v[206:209], v249 offset:41504
	v_mfma_f32_32x32x16_bf16 v[98:113], v[198:201], v[214:217], v[98:113]
	ds_read_b128 v[210:213], v248 offset:41504
	s_waitcnt vmcnt(15)
	ds_write_b128 v250, v[2:5]
	s_waitcnt lgkmcnt(6)
	v_mfma_f32_32x32x16_bf16 v[50:65], v[194:197], v[228:231], v[50:65]
	ds_read_b128 v[214:217], v248 offset:46112
	v_mfma_f32_32x32x16_bf16 v[66:81], v[198:201], v[228:231], v[66:81]
	global_load_dwordx4 v[2:5], v227, s[74:75] offset:1536
	s_waitcnt lgkmcnt(6)
	v_mfma_f32_32x32x16_bf16 v[18:33], v[194:197], v[232:235], v[18:33]
	ds_read_b128 v[228:231], v248 offset:50720
	s_waitcnt vmcnt(15)
	ds_write_b128 v251, v[162:165]
	v_mfma_f32_32x32x16_bf16 v[34:49], v[198:201], v[232:235], v[34:49]
	s_waitcnt lgkmcnt(6)
	v_mfma_f32_32x32x16_bf16 v[114:129], v[202:205], v[236:239], v[114:129]
	ds_read_b128 v[194:197], v249 offset:36928
	global_load_dwordx4 v[162:165], v227, s[82:83] offset:1536
	s_waitcnt lgkmcnt(6)
	v_mfma_f32_32x32x16_bf16 v[130:145], v[206:209], v[236:239], v[130:145]
	ds_read_b128 v[232:235], v248 offset:36928
	s_waitcnt vmcnt(15)
	ds_write_b128 v250, v[6:9] offset:9216
	s_waitcnt lgkmcnt(7)
	v_mfma_f32_32x32x16_bf16 v[82:97], v[202:205], v[210:213], v[82:97]
	ds_read_b128 v[198:201], v249 offset:41536
	v_mfma_f32_32x32x16_bf16 v[98:113], v[206:209], v[210:213], v[98:113]
	ds_read_b128 v[236:239], v248 offset:41536
	global_load_dwordx4 v[6:9], v227, s[76:77] offset:1536
	s_waitcnt lgkmcnt(7)
	v_mfma_f32_32x32x16_bf16 v[50:65], v[202:205], v[214:217], v[50:65]
	ds_read_b128 v[210:213], v248 offset:46144
	s_waitcnt vmcnt(15)
	ds_write_b128 v251, v[166:169] offset:9216
	v_mfma_f32_32x32x16_bf16 v[66:81], v[206:209], v[214:217], v[66:81]
	s_waitcnt lgkmcnt(8)
	v_mfma_f32_32x32x16_bf16 v[18:33], v[202:205], v[228:231], v[18:33]
	ds_read_b128 v[214:217], v248 offset:50752
	global_load_dwordx4 v[166:169], v227, s[84:85] offset:1536
	v_mfma_f32_32x32x16_bf16 v[34:49], v[206:209], v[228:231], v[34:49]
	s_waitcnt vmcnt(15)
	ds_write_b128 v250, v[10:13] offset:18432
	s_waitcnt lgkmcnt(7)
	v_mfma_f32_32x32x16_bf16 v[114:129], v[194:197], v[232:235], v[114:129]
	ds_read_b128 v[202:205], v249 offset:36960
	s_waitcnt lgkmcnt(6)
	v_mfma_f32_32x32x16_bf16 v[130:145], v[198:201], v[232:235], v[130:145]
	ds_read_b128 v[228:231], v248 offset:36960
	global_load_dwordx4 v[10:13], v227, s[78:79] offset:1536
	s_waitcnt lgkmcnt(6)
	v_mfma_f32_32x32x16_bf16 v[82:97], v[194:197], v[236:239], v[82:97]
	ds_read_b128 v[206:209], v249 offset:41568
	s_waitcnt vmcnt(15)
	ds_write_b128 v251, v[170:173] offset:18432
	v_mfma_f32_32x32x16_bf16 v[98:113], v[198:201], v[236:239], v[98:113]
	ds_read_b128 v[232:235], v248 offset:41568
	s_waitcnt lgkmcnt(8)
	v_mfma_f32_32x32x16_bf16 v[50:65], v[194:197], v[210:213], v[50:65]
	ds_read_b128 v[236:239], v248 offset:46176
	global_load_dwordx4 v[170:173], v227, s[86:87] offset:1536
	v_mfma_f32_32x32x16_bf16 v[66:81], v[198:201], v[210:213], v[66:81]
	s_waitcnt vmcnt(15)
	ds_write_b128 v250, v[14:17] offset:27648
	s_waitcnt lgkmcnt(8)
	v_mfma_f32_32x32x16_bf16 v[18:33], v[194:197], v[214:217], v[18:33]
	ds_read_b128 v[210:213], v248 offset:50784
	v_mfma_f32_32x32x16_bf16 v[34:49], v[198:201], v[214:217], v[34:49]
	global_load_dwordx4 v[14:17], v227, s[80:81] offset:1536
	s_waitcnt lgkmcnt(6)
	v_mfma_f32_32x32x16_bf16 v[114:129], v[202:205], v[228:231], v[114:129]
	s_waitcnt vmcnt(15)
	ds_write_b128 v251, v[174:177] offset:27648
	s_waitcnt lgkmcnt(6)
	v_mfma_f32_32x32x16_bf16 v[130:145], v[206:209], v[228:231], v[130:145]
	s_waitcnt lgkmcnt(4)
	v_mfma_f32_32x32x16_bf16 v[82:97], v[202:205], v[232:235], v[82:97]
	global_load_dwordx4 v[174:177], v227, s[92:93] offset:1536
	v_mfma_f32_32x32x16_bf16 v[98:113], v[206:209], v[232:235], v[98:113]
	s_waitcnt lgkmcnt(3)
	v_mfma_f32_32x32x16_bf16 v[50:65], v[202:205], v[236:239], v[50:65]
	v_mfma_f32_32x32x16_bf16 v[66:81], v[206:209], v[236:239], v[66:81]
	s_waitcnt lgkmcnt(1)
	v_mfma_f32_32x32x16_bf16 v[18:33], v[202:205], v[210:213], v[18:33]
	v_mfma_f32_32x32x16_bf16 v[34:49], v[206:209], v[210:213], v[34:49]
	s_waitcnt lgkmcnt(0)
	s_barrier
;     ...
;   for (int kt = 0; kt < nk; ++kt) {
;     __syncthreads();
;     if (kt + 1 < nk) {
;       u16* aw = As0 + ((kt + 1) & 1) * 256 * LD;
;       u16* bw = Bs0 + ((kt + 1) & 1) * 256 * LD;
; #pragma unroll
;       for (int i = 0; i < 4; ++i) { *(u32x4*)(aw + (srow + 64 * i) * LD + skc * 8) = ra[i]; *(u32x4*)(bw + (srow + 64 * i) * LD + skc * 8) = rb[i]; }
;     }
;     if (kt + 2 < nk) {
; #pragma unroll
;       for (int i = 0; i < 4; ++i) { ra[i] = *(const u32x4*)(Ag + (size_t)(64 * i) * K + (kt + 2) * 64); rb[i] = *(const u32x4*)(Bg[i] + (kt + 2) * 64); }
;     }
;     __builtin_amdgcn_sched_barrier(0);
;     const u16* as = As0 + (kt & 1) * 256 * LD + (wr * 128 + l31) * LD + h * 8;
;     const u16* bs = Bs0 + (kt & 1) * 256 * LD + (wc * 64 + l31) * LD + h * 8;
;     if (domma)
; #pragma unroll
;     for (int ks = 0; ks < 4; ++ks) {
;       bf16x8 wf[2], xf[4];
; #pragma unroll
;       for (int ct = 0; ct < 2; ++ct) wf[ct] = *(const bf16x8*)(bs + ct * 32 * LD + ks * 16);
; #pragma unroll
;       for (int tt = 0; tt < 4; ++tt) xf[tt] = *(const bf16x8*)(as + tt * 32 * LD + ks * 16);
; #pragma unroll
;       for (int ct = 0; ct < 2; ++ct)
; #pragma unroll
;         for (int tt = 0; tt < 4; ++tt) acc[ct][tt] = __builtin_amdgcn_mfma_f32_32x32x16_bf16(wf[ct], xf[tt], acc[ct][tt], 0, 0, 0);
;     }
;     __builtin_amdgcn_sched_barrier(0);
;   }
	ds_read_b128 v[194:197], v249
	ds_read_b128 v[210:213], v248
	ds_read_b128 v[198:201], v249 offset:4608
	ds_read_b128 v[214:217], v248 offset:4608
	ds_read_b128 v[228:231], v248 offset:9216
	ds_read_b128 v[232:235], v248 offset:13824
	s_waitcnt lgkmcnt(4)
	v_mfma_f32_32x32x16_bf16 v[114:129], v[194:197], v[210:213], v[114:129]
	ds_read_b128 v[202:205], v249 offset:32
	s_waitcnt lgkmcnt(4)
	v_mfma_f32_32x32x16_bf16 v[130:145], v[198:201], v[210:213], v[130:145]
	ds_read_b128 v[236:239], v248 offset:32
	s_waitcnt lgkmcnt(4)
	v_mfma_f32_32x32x16_bf16 v[82:97], v[194:197], v[214:217], v[82:97]
	ds_read_b128 v[206:209], v249 offset:4640
	v_mfma_f32_32x32x16_bf16 v[98:113], v[198:201], v[214:217], v[98:113]
	ds_read_b128 v[210:213], v248 offset:4640
	s_waitcnt vmcnt(15)
	ds_write_b128 v250, v[146:149] offset:36864
	s_waitcnt lgkmcnt(6)
	v_mfma_f32_32x32x16_bf16 v[50:65], v[194:197], v[228:231], v[50:65]
	ds_read_b128 v[214:217], v248 offset:9248
	v_mfma_f32_32x32x16_bf16 v[66:81], v[198:201], v[228:231], v[66:81]
	global_load_dwordx4 v[146:149], v227, s[74:75] offset:1664
	s_waitcnt lgkmcnt(6)
	v_mfma_f32_32x32x16_bf16 v[18:33], v[194:197], v[232:235], v[18:33]
	ds_read_b128 v[228:231], v248 offset:13856
	s_waitcnt vmcnt(15)
	ds_write_b128 v251, v[178:181] offset:36864
	v_mfma_f32_32x32x16_bf16 v[34:49], v[198:201], v[232:235], v[34:49]
	s_waitcnt lgkmcnt(6)
	v_mfma_f32_32x32x16_bf16 v[114:129], v[202:205], v[236:239], v[114:129]
	ds_read_b128 v[194:197], v249 offset:64
	global_load_dwordx4 v[178:181], v227, s[82:83] offset:1664
	s_waitcnt lgkmcnt(6)
	v_mfma_f32_32x32x16_bf16 v[130:145], v[206:209], v[236:239], v[130:145]
	ds_read_b128 v[232:235], v248 offset:64
	s_waitcnt vmcnt(15)
	ds_write_b128 v250, v[150:153] offset:46080
	s_waitcnt lgkmcnt(7)
	v_mfma_f32_32x32x16_bf16 v[82:97], v[202:205], v[210:213], v[82:97]
	ds_read_b128 v[198:201], v249 offset:4672
	v_mfma_f32_32x32x16_bf16 v[98:113], v[206:209], v[210:213], v[98:113]
	ds_read_b128 v[236:239], v248 offset:4672
	global_load_dwordx4 v[150:153], v227, s[76:77] offset:1664
	s_waitcnt lgkmcnt(7)
	v_mfma_f32_32x32x16_bf16 v[50:65], v[202:205], v[214:217], v[50:65]
	ds_read_b128 v[210:213], v248 offset:9280
	s_waitcnt vmcnt(15)
	ds_write_b128 v251, v[182:185] offset:46080
	v_mfma_f32_32x32x16_bf16 v[66:81], v[206:209], v[214:217], v[66:81]
	s_waitcnt lgkmcnt(8)
	v_mfma_f32_32x32x16_bf16 v[18:33], v[202:205], v[228:231], v[18:33]
	ds_read_b128 v[214:217], v248 offset:13888
	global_load_dwordx4 v[182:185], v227, s[84:85] offset:1664
	v_mfma_f32_32x32x16_bf16 v[34:49], v[206:209], v[228:231], v[34:49]
	s_waitcnt vmcnt(15)
	ds_write_b128 v250, v[154:157] offset:55296
	s_waitcnt lgkmcnt(7)
	v_mfma_f32_32x32x16_bf16 v[114:129], v[194:197], v[232:235], v[114:129]
	ds_read_b128 v[202:205], v249 offset:96
	s_waitcnt lgkmcnt(6)
	v_mfma_f32_32x32x16_bf16 v[130:145], v[198:201], v[232:235], v[130:145]
	ds_read_b128 v[228:231], v248 offset:96
	global_load_dwordx4 v[154:157], v227, s[78:79] offset:1664
	s_waitcnt lgkmcnt(6)
	v_mfma_f32_32x32x16_bf16 v[82:97], v[194:197], v[236:239], v[82:97]
	ds_read_b128 v[206:209], v249 offset:4704
	s_waitcnt vmcnt(15)
	ds_write_b128 v251, v[186:189] offset:55296
	v_mfma_f32_32x32x16_bf16 v[98:113], v[198:201], v[236:239], v[98:113]
	ds_read_b128 v[232:235], v248 offset:4704
	s_waitcnt lgkmcnt(8)
	v_mfma_f32_32x32x16_bf16 v[50:65], v[194:197], v[210:213], v[50:65]
	ds_read_b128 v[236:239], v248 offset:9312
	global_load_dwordx4 v[186:189], v227, s[86:87] offset:1664
	v_mfma_f32_32x32x16_bf16 v[66:81], v[198:201], v[210:213], v[66:81]
	s_waitcnt vmcnt(15)
	ds_write_b128 v250, v[158:161] offset:64512
	s_waitcnt lgkmcnt(8)
	v_mfma_f32_32x32x16_bf16 v[18:33], v[194:197], v[214:217], v[18:33]
	ds_read_b128 v[210:213], v248 offset:13920
	v_mfma_f32_32x32x16_bf16 v[34:49], v[198:201], v[214:217], v[34:49]
	global_load_dwordx4 v[158:161], v227, s[80:81] offset:1664
	s_waitcnt lgkmcnt(6)
	v_mfma_f32_32x32x16_bf16 v[114:129], v[202:205], v[228:231], v[114:129]
	s_waitcnt vmcnt(15)
	ds_write_b128 v251, v[190:193] offset:64512
	s_waitcnt lgkmcnt(6)
	v_mfma_f32_32x32x16_bf16 v[130:145], v[206:209], v[228:231], v[130:145]
	s_waitcnt lgkmcnt(4)
	v_mfma_f32_32x32x16_bf16 v[82:97], v[202:205], v[232:235], v[82:97]
	global_load_dwordx4 v[190:193], v227, s[92:93] offset:1664
	v_mfma_f32_32x32x16_bf16 v[98:113], v[206:209], v[232:235], v[98:113]
	s_waitcnt lgkmcnt(3)
	v_mfma_f32_32x32x16_bf16 v[50:65], v[202:205], v[236:239], v[50:65]
	v_mfma_f32_32x32x16_bf16 v[66:81], v[206:209], v[236:239], v[66:81]
	s_waitcnt lgkmcnt(1)
	v_mfma_f32_32x32x16_bf16 v[18:33], v[202:205], v[210:213], v[18:33]
	v_mfma_f32_32x32x16_bf16 v[34:49], v[206:209], v[210:213], v[34:49]
	s_waitcnt lgkmcnt(0)
	s_barrier
;     ...
;   for (int kt = 0; kt < nk; ++kt) {
;     __syncthreads();
;     if (kt + 1 < nk) {
;       u16* aw = As0 + ((kt + 1) & 1) * 256 * LD;
;       u16* bw = Bs0 + ((kt + 1) & 1) * 256 * LD;
; #pragma unroll
;       for (int i = 0; i < 4; ++i) { *(u32x4*)(aw + (srow + 64 * i) * LD + skc * 8) = ra[i]; *(u32x4*)(bw + (srow + 64 * i) * LD + skc * 8) = rb[i]; }
;     }
;     if (kt + 2 < nk) {
; #pragma unroll
;       for (int i = 0; i < 4; ++i) { ra[i] = *(const u32x4*)(Ag + (size_t)(64 * i) * K + (kt + 2) * 64); rb[i] = *(const u32x4*)(Bg[i] + (kt + 2) * 64); }
;     }
;     __builtin_amdgcn_sched_barrier(0);
;     const u16* as = As0 + (kt & 1) * 256 * LD + (wr * 128 + l31) * LD + h * 8;
;     const u16* bs = Bs0 + (kt & 1) * 256 * LD + (wc * 64 + l31) * LD + h * 8;
;     if (domma)
; #pragma unroll
;     for (int ks = 0; ks < 4; ++ks) {
;       bf16x8 wf[2], xf[4];
; #pragma unroll
;       for (int ct = 0; ct < 2; ++ct) wf[ct] = *(const bf16x8*)(bs + ct * 32 * LD + ks * 16);
; #pragma unroll
;       for (int tt = 0; tt < 4; ++tt) xf[tt] = *(const bf16x8*)(as + tt * 32 * LD + ks * 16);
; #pragma unroll
;       for (int ct = 0; ct < 2; ++ct)
; #pragma unroll
;         for (int tt = 0; tt < 4; ++tt) acc[ct][tt] = __builtin_amdgcn_mfma_f32_32x32x16_bf16(wf[ct], xf[tt], acc[ct][tt], 0, 0, 0);
;     }
;     __builtin_amdgcn_sched_barrier(0);
;   }
	ds_read_b128 v[194:197], v249 offset:36864
	ds_read_b128 v[210:213], v248 offset:36864
	ds_read_b128 v[198:201], v249 offset:41472
	ds_read_b128 v[214:217], v248 offset:41472
	ds_read_b128 v[228:231], v248 offset:46080
	ds_read_b128 v[232:235], v248 offset:50688
	s_waitcnt lgkmcnt(4)
	v_mfma_f32_32x32x16_bf16 v[114:129], v[194:197], v[210:213], v[114:129]
	ds_read_b128 v[202:205], v249 offset:36896
	s_waitcnt lgkmcnt(4)
	v_mfma_f32_32x32x16_bf16 v[130:145], v[198:201], v[210:213], v[130:145]
	ds_read_b128 v[236:239], v248 offset:36896
	s_waitcnt lgkmcnt(4)
	v_mfma_f32_32x32x16_bf16 v[82:97], v[194:197], v[214:217], v[82:97]
	ds_read_b128 v[206:209], v249 offset:41504
	v_mfma_f32_32x32x16_bf16 v[98:113], v[198:201], v[214:217], v[98:113]
	ds_read_b128 v[210:213], v248 offset:41504
	s_waitcnt vmcnt(15)
	ds_write_b128 v250, v[2:5]
	s_waitcnt lgkmcnt(6)
	v_mfma_f32_32x32x16_bf16 v[50:65], v[194:197], v[228:231], v[50:65]
	ds_read_b128 v[214:217], v248 offset:46112
	v_mfma_f32_32x32x16_bf16 v[66:81], v[198:201], v[228:231], v[66:81]
	global_load_dwordx4 v[2:5], v227, s[74:75] offset:1792
	s_waitcnt lgkmcnt(6)
	v_mfma_f32_32x32x16_bf16 v[18:33], v[194:197], v[232:235], v[18:33]
	ds_read_b128 v[228:231], v248 offset:50720
	s_waitcnt vmcnt(15)
	ds_write_b128 v251, v[162:165]
	v_mfma_f32_32x32x16_bf16 v[34:49], v[198:201], v[232:235], v[34:49]
	s_waitcnt lgkmcnt(6)
	v_mfma_f32_32x32x16_bf16 v[114:129], v[202:205], v[236:239], v[114:129]
	ds_read_b128 v[194:197], v249 offset:36928
	global_load_dwordx4 v[162:165], v227, s[82:83] offset:1792
	s_waitcnt lgkmcnt(6)
	v_mfma_f32_32x32x16_bf16 v[130:145], v[206:209], v[236:239], v[130:145]
	ds_read_b128 v[232:235], v248 offset:36928
	s_waitcnt vmcnt(15)
	ds_write_b128 v250, v[6:9] offset:9216
	s_waitcnt lgkmcnt(7)
	v_mfma_f32_32x32x16_bf16 v[82:97], v[202:205], v[210:213], v[82:97]
	ds_read_b128 v[198:201], v249 offset:41536
	v_mfma_f32_32x32x16_bf16 v[98:113], v[206:209], v[210:213], v[98:113]
	ds_read_b128 v[236:239], v248 offset:41536
	global_load_dwordx4 v[6:9], v227, s[76:77] offset:1792
	s_waitcnt lgkmcnt(7)
	v_mfma_f32_32x32x16_bf16 v[50:65], v[202:205], v[214:217], v[50:65]
	ds_read_b128 v[210:213], v248 offset:46144
	s_waitcnt vmcnt(15)
	ds_write_b128 v251, v[166:169] offset:9216
	v_mfma_f32_32x32x16_bf16 v[66:81], v[206:209], v[214:217], v[66:81]
	s_waitcnt lgkmcnt(8)
	v_mfma_f32_32x32x16_bf16 v[18:33], v[202:205], v[228:231], v[18:33]
	ds_read_b128 v[214:217], v248 offset:50752
	global_load_dwordx4 v[166:169], v227, s[84:85] offset:1792
	v_mfma_f32_32x32x16_bf16 v[34:49], v[206:209], v[228:231], v[34:49]
	s_waitcnt vmcnt(15)
	ds_write_b128 v250, v[10:13] offset:18432
	s_waitcnt lgkmcnt(7)
	v_mfma_f32_32x32x16_bf16 v[114:129], v[194:197], v[232:235], v[114:129]
	ds_read_b128 v[202:205], v249 offset:36960
	s_waitcnt lgkmcnt(6)
	v_mfma_f32_32x32x16_bf16 v[130:145], v[198:201], v[232:235], v[130:145]
	ds_read_b128 v[228:231], v248 offset:36960
	global_load_dwordx4 v[10:13], v227, s[78:79] offset:1792
	s_waitcnt lgkmcnt(6)
	v_mfma_f32_32x32x16_bf16 v[82:97], v[194:197], v[236:239], v[82:97]
	ds_read_b128 v[206:209], v249 offset:41568
	s_waitcnt vmcnt(15)
	ds_write_b128 v251, v[170:173] offset:18432
	v_mfma_f32_32x32x16_bf16 v[98:113], v[198:201], v[236:239], v[98:113]
	ds_read_b128 v[232:235], v248 offset:41568
	s_waitcnt lgkmcnt(8)
	v_mfma_f32_32x32x16_bf16 v[50:65], v[194:197], v[210:213], v[50:65]
	ds_read_b128 v[236:239], v248 offset:46176
	global_load_dwordx4 v[170:173], v227, s[86:87] offset:1792
	v_mfma_f32_32x32x16_bf16 v[66:81], v[198:201], v[210:213], v[66:81]
	s_waitcnt vmcnt(15)
	ds_write_b128 v250, v[14:17] offset:27648
	s_waitcnt lgkmcnt(8)
	v_mfma_f32_32x32x16_bf16 v[18:33], v[194:197], v[214:217], v[18:33]
	ds_read_b128 v[210:213], v248 offset:50784
	v_mfma_f32_32x32x16_bf16 v[34:49], v[198:201], v[214:217], v[34:49]
	global_load_dwordx4 v[14:17], v227, s[80:81] offset:1792
	s_waitcnt lgkmcnt(6)
	v_mfma_f32_32x32x16_bf16 v[114:129], v[202:205], v[228:231], v[114:129]
	s_waitcnt vmcnt(15)
	ds_write_b128 v251, v[174:177] offset:27648
	s_waitcnt lgkmcnt(6)
	v_mfma_f32_32x32x16_bf16 v[130:145], v[206:209], v[228:231], v[130:145]
	s_waitcnt lgkmcnt(4)
	v_mfma_f32_32x32x16_bf16 v[82:97], v[202:205], v[232:235], v[82:97]
	global_load_dwordx4 v[174:177], v227, s[92:93] offset:1792
	v_mfma_f32_32x32x16_bf16 v[98:113], v[206:209], v[232:235], v[98:113]
	s_waitcnt lgkmcnt(3)
	v_mfma_f32_32x32x16_bf16 v[50:65], v[202:205], v[236:239], v[50:65]
	v_mfma_f32_32x32x16_bf16 v[66:81], v[206:209], v[236:239], v[66:81]
	s_waitcnt lgkmcnt(1)
	v_mfma_f32_32x32x16_bf16 v[18:33], v[202:205], v[210:213], v[18:33]
	v_mfma_f32_32x32x16_bf16 v[34:49], v[206:209], v[210:213], v[34:49]
	s_waitcnt lgkmcnt(0)
	s_barrier
;     ...
;   for (int kt = 0; kt < nk; ++kt) {
;     __syncthreads();
;     if (kt + 1 < nk) {
;       u16* aw = As0 + ((kt + 1) & 1) * 256 * LD;
;       u16* bw = Bs0 + ((kt + 1) & 1) * 256 * LD;
; #pragma unroll
;       for (int i = 0; i < 4; ++i) { *(u32x4*)(aw + (srow + 64 * i) * LD + skc * 8) = ra[i]; *(u32x4*)(bw + (srow + 64 * i) * LD + skc * 8) = rb[i]; }
;     }
;     if (kt + 2 < nk) {
; #pragma unroll
;       for (int i = 0; i < 4; ++i) { ra[i] = *(const u32x4*)(Ag + (size_t)(64 * i) * K + (kt + 2) * 64); rb[i] = *(const u32x4*)(Bg[i] + (kt + 2) * 64); }
;     }
;     __builtin_amdgcn_sched_barrier(0);
;     const u16* as = As0 + (kt & 1) * 256 * LD + (wr * 128 + l31) * LD + h * 8;
;     const u16* bs = Bs0 + (kt & 1) * 256 * LD + (wc * 64 + l31) * LD + h * 8;
;     if (domma)
; #pragma unroll
;     for (int ks = 0; ks < 4; ++ks) {
;       bf16x8 wf[2], xf[4];
; #pragma unroll
;       for (int ct = 0; ct < 2; ++ct) wf[ct] = *(const bf16x8*)(bs + ct * 32 * LD + ks * 16);
; #pragma unroll
;       for (int tt = 0; tt < 4; ++tt) xf[tt] = *(const bf16x8*)(as + tt * 32 * LD + ks * 16);
; #pragma unroll
;       for (int ct = 0; ct < 2; ++ct)
; #pragma unroll
;         for (int tt = 0; tt < 4; ++tt) acc[ct][tt] = __builtin_amdgcn_mfma_f32_32x32x16_bf16(wf[ct], xf[tt], acc[ct][tt], 0, 0, 0);
;     }
;     __builtin_amdgcn_sched_barrier(0);
;   }
	ds_read_b128 v[194:197], v249
	ds_read_b128 v[210:213], v248
	ds_read_b128 v[198:201], v249 offset:4608
	ds_read_b128 v[214:217], v248 offset:4608
	ds_read_b128 v[228:231], v248 offset:9216
	ds_read_b128 v[232:235], v248 offset:13824
	s_waitcnt lgkmcnt(4)
	v_mfma_f32_32x32x16_bf16 v[114:129], v[194:197], v[210:213], v[114:129]
	ds_read_b128 v[202:205], v249 offset:32
	s_waitcnt lgkmcnt(4)
	v_mfma_f32_32x32x16_bf16 v[130:145], v[198:201], v[210:213], v[130:145]
	ds_read_b128 v[236:239], v248 offset:32
	s_waitcnt lgkmcnt(4)
	v_mfma_f32_32x32x16_bf16 v[82:97], v[194:197], v[214:217], v[82:97]
	ds_read_b128 v[206:209], v249 offset:4640
	v_mfma_f32_32x32x16_bf16 v[98:113], v[198:201], v[214:217], v[98:113]
	ds_read_b128 v[210:213], v248 offset:4640
	s_waitcnt vmcnt(15)
	ds_write_b128 v250, v[146:149] offset:36864
	s_waitcnt lgkmcnt(6)
	v_mfma_f32_32x32x16_bf16 v[50:65], v[194:197], v[228:231], v[50:65]
	ds_read_b128 v[214:217], v248 offset:9248
	v_mfma_f32_32x32x16_bf16 v[66:81], v[198:201], v[228:231], v[66:81]
	global_load_dwordx4 v[146:149], v227, s[74:75] offset:1920
	s_waitcnt lgkmcnt(6)
	v_mfma_f32_32x32x16_bf16 v[18:33], v[194:197], v[232:235], v[18:33]
	ds_read_b128 v[228:231], v248 offset:13856
	s_waitcnt vmcnt(15)
	ds_write_b128 v251, v[178:181] offset:36864
	v_mfma_f32_32x32x16_bf16 v[34:49], v[198:201], v[232:235], v[34:49]
	s_waitcnt lgkmcnt(6)
	v_mfma_f32_32x32x16_bf16 v[114:129], v[202:205], v[236:239], v[114:129]
	ds_read_b128 v[194:197], v249 offset:64
	global_load_dwordx4 v[178:181], v227, s[82:83] offset:1920
	s_waitcnt lgkmcnt(6)
	v_mfma_f32_32x32x16_bf16 v[130:145], v[206:209], v[236:239], v[130:145]
	ds_read_b128 v[232:235], v248 offset:64
	s_waitcnt vmcnt(15)
	ds_write_b128 v250, v[150:153] offset:46080
	s_waitcnt lgkmcnt(7)
	v_mfma_f32_32x32x16_bf16 v[82:97], v[202:205], v[210:213], v[82:97]
	ds_read_b128 v[198:201], v249 offset:4672
	v_mfma_f32_32x32x16_bf16 v[98:113], v[206:209], v[210:213], v[98:113]
	ds_read_b128 v[236:239], v248 offset:4672
	global_load_dwordx4 v[150:153], v227, s[76:77] offset:1920
	s_waitcnt lgkmcnt(7)
	v_mfma_f32_32x32x16_bf16 v[50:65], v[202:205], v[214:217], v[50:65]
	ds_read_b128 v[210:213], v248 offset:9280
	s_waitcnt vmcnt(15)
	ds_write_b128 v251, v[182:185] offset:46080
	v_mfma_f32_32x32x16_bf16 v[66:81], v[206:209], v[214:217], v[66:81]
	s_waitcnt lgkmcnt(8)
	v_mfma_f32_32x32x16_bf16 v[18:33], v[202:205], v[228:231], v[18:33]
	ds_read_b128 v[214:217], v248 offset:13888
	global_load_dwordx4 v[182:185], v227, s[84:85] offset:1920
	v_mfma_f32_32x32x16_bf16 v[34:49], v[206:209], v[228:231], v[34:49]
	s_waitcnt vmcnt(15)
	ds_write_b128 v250, v[154:157] offset:55296
	s_waitcnt lgkmcnt(7)
	v_mfma_f32_32x32x16_bf16 v[114:129], v[194:197], v[232:235], v[114:129]
	ds_read_b128 v[202:205], v249 offset:96
	s_waitcnt lgkmcnt(6)
	v_mfma_f32_32x32x16_bf16 v[130:145], v[198:201], v[232:235], v[130:145]
	ds_read_b128 v[228:231], v248 offset:96
	global_load_dwordx4 v[154:157], v227, s[78:79] offset:1920
	s_waitcnt lgkmcnt(6)
	v_mfma_f32_32x32x16_bf16 v[82:97], v[194:197], v[236:239], v[82:97]
	ds_read_b128 v[206:209], v249 offset:4704
	s_waitcnt vmcnt(15)
	ds_write_b128 v251, v[186:189] offset:55296
	v_mfma_f32_32x32x16_bf16 v[98:113], v[198:201], v[236:239], v[98:113]
	ds_read_b128 v[232:235], v248 offset:4704
	s_waitcnt lgkmcnt(8)
	v_mfma_f32_32x32x16_bf16 v[50:65], v[194:197], v[210:213], v[50:65]
	ds_read_b128 v[236:239], v248 offset:9312
	global_load_dwordx4 v[186:189], v227, s[86:87] offset:1920
	v_mfma_f32_32x32x16_bf16 v[66:81], v[198:201], v[210:213], v[66:81]
	s_waitcnt vmcnt(15)
	ds_write_b128 v250, v[158:161] offset:64512
	s_waitcnt lgkmcnt(8)
	v_mfma_f32_32x32x16_bf16 v[18:33], v[194:197], v[214:217], v[18:33]
	ds_read_b128 v[210:213], v248 offset:13920
	v_mfma_f32_32x32x16_bf16 v[34:49], v[198:201], v[214:217], v[34:49]
	global_load_dwordx4 v[158:161], v227, s[80:81] offset:1920
	s_waitcnt lgkmcnt(6)
	v_mfma_f32_32x32x16_bf16 v[114:129], v[202:205], v[228:231], v[114:129]
	s_waitcnt vmcnt(15)
	ds_write_b128 v251, v[190:193] offset:64512
	s_waitcnt lgkmcnt(6)
	v_mfma_f32_32x32x16_bf16 v[130:145], v[206:209], v[228:231], v[130:145]
	s_waitcnt lgkmcnt(4)
	v_mfma_f32_32x32x16_bf16 v[82:97], v[202:205], v[232:235], v[82:97]
	global_load_dwordx4 v[190:193], v227, s[92:93] offset:1920
	v_mfma_f32_32x32x16_bf16 v[98:113], v[206:209], v[232:235], v[98:113]
	s_waitcnt lgkmcnt(3)
	v_mfma_f32_32x32x16_bf16 v[50:65], v[202:205], v[236:239], v[50:65]
	v_mfma_f32_32x32x16_bf16 v[66:81], v[206:209], v[236:239], v[66:81]
	s_waitcnt lgkmcnt(1)
	v_mfma_f32_32x32x16_bf16 v[18:33], v[202:205], v[210:213], v[18:33]
	v_mfma_f32_32x32x16_bf16 v[34:49], v[206:209], v[210:213], v[34:49]
	s_waitcnt lgkmcnt(0)
	s_barrier
;     ...
;   for (int kt = 0; kt < nk; ++kt) {
;     __syncthreads();
;     if (kt + 1 < nk) {
;       u16* aw = As0 + ((kt + 1) & 1) * 256 * LD;
;       u16* bw = Bs0 + ((kt + 1) & 1) * 256 * LD;
; #pragma unroll
;       for (int i = 0; i < 4; ++i) { *(u32x4*)(aw + (srow + 64 * i) * LD + skc * 8) = ra[i]; *(u32x4*)(bw + (srow + 64 * i) * LD + skc * 8) = rb[i]; }
;     }
;     if (kt + 2 < nk) {
; #pragma unroll
;       for (int i = 0; i < 4; ++i) { ra[i] = *(const u32x4*)(Ag + (size_t)(64 * i) * K + (kt + 2) * 64); rb[i] = *(const u32x4*)(Bg[i] + (kt + 2) * 64); }
;     }
;     __builtin_amdgcn_sched_barrier(0);
;     const u16* as = As0 + (kt & 1) * 256 * LD + (wr * 128 + l31) * LD + h * 8;
;     const u16* bs = Bs0 + (kt & 1) * 256 * LD + (wc * 64 + l31) * LD + h * 8;
;     if (domma)
; #pragma unroll
;     for (int ks = 0; ks < 4; ++ks) {
;       bf16x8 wf[2], xf[4];
; #pragma unroll
;       for (int ct = 0; ct < 2; ++ct) wf[ct] = *(const bf16x8*)(bs + ct * 32 * LD + ks * 16);
; #pragma unroll
;       for (int tt = 0; tt < 4; ++tt) xf[tt] = *(const bf16x8*)(as + tt * 32 * LD + ks * 16);
; #pragma unroll
;       for (int ct = 0; ct < 2; ++ct)
; #pragma unroll
;         for (int tt = 0; tt < 4; ++tt) acc[ct][tt] = __builtin_amdgcn_mfma_f32_32x32x16_bf16(wf[ct], xf[tt], acc[ct][tt], 0, 0, 0);
;     }
;     __builtin_amdgcn_sched_barrier(0);
;   }
	ds_read_b128 v[194:197], v249 offset:36864
	ds_read_b128 v[210:213], v248 offset:36864
	ds_read_b128 v[198:201], v249 offset:41472
	ds_read_b128 v[214:217], v248 offset:41472
	ds_read_b128 v[228:231], v248 offset:46080
	ds_read_b128 v[232:235], v248 offset:50688
	s_waitcnt lgkmcnt(4)
	v_mfma_f32_32x32x16_bf16 v[114:129], v[194:197], v[210:213], v[114:129]
	ds_read_b128 v[202:205], v249 offset:36896
	s_waitcnt lgkmcnt(4)
	v_mfma_f32_32x32x16_bf16 v[130:145], v[198:201], v[210:213], v[130:145]
	ds_read_b128 v[236:239], v248 offset:36896
	s_waitcnt lgkmcnt(4)
	v_mfma_f32_32x32x16_bf16 v[82:97], v[194:197], v[214:217], v[82:97]
	ds_read_b128 v[206:209], v249 offset:41504
	v_mfma_f32_32x32x16_bf16 v[98:113], v[198:201], v[214:217], v[98:113]
	ds_read_b128 v[210:213], v248 offset:41504
	s_waitcnt vmcnt(15)
	ds_write_b128 v250, v[2:5]
	s_waitcnt lgkmcnt(6)
	v_mfma_f32_32x32x16_bf16 v[50:65], v[194:197], v[228:231], v[50:65]
	ds_read_b128 v[214:217], v248 offset:46112
	v_mfma_f32_32x32x16_bf16 v[66:81], v[198:201], v[228:231], v[66:81]
	s_waitcnt lgkmcnt(6)
	v_mfma_f32_32x32x16_bf16 v[18:33], v[194:197], v[232:235], v[18:33]
	ds_read_b128 v[228:231], v248 offset:50720
	s_waitcnt vmcnt(14)
	ds_write_b128 v251, v[162:165]
	v_mfma_f32_32x32x16_bf16 v[34:49], v[198:201], v[232:235], v[34:49]
	s_waitcnt lgkmcnt(6)
	v_mfma_f32_32x32x16_bf16 v[114:129], v[202:205], v[236:239], v[114:129]
	ds_read_b128 v[194:197], v249 offset:36928
	s_waitcnt lgkmcnt(6)
	v_mfma_f32_32x32x16_bf16 v[130:145], v[206:209], v[236:239], v[130:145]
	ds_read_b128 v[232:235], v248 offset:36928
	s_waitcnt vmcnt(13)
	ds_write_b128 v250, v[6:9] offset:9216
	s_waitcnt lgkmcnt(7)
	v_mfma_f32_32x32x16_bf16 v[82:97], v[202:205], v[210:213], v[82:97]
	ds_read_b128 v[198:201], v249 offset:41536
	v_mfma_f32_32x32x16_bf16 v[98:113], v[206:209], v[210:213], v[98:113]
	ds_read_b128 v[236:239], v248 offset:41536
	s_waitcnt lgkmcnt(7)
	v_mfma_f32_32x32x16_bf16 v[50:65], v[202:205], v[214:217], v[50:65]
	ds_read_b128 v[210:213], v248 offset:46144
	s_waitcnt vmcnt(12)
	ds_write_b128 v251, v[166:169] offset:9216
	v_mfma_f32_32x32x16_bf16 v[66:81], v[206:209], v[214:217], v[66:81]
	s_waitcnt lgkmcnt(8)
	v_mfma_f32_32x32x16_bf16 v[18:33], v[202:205], v[228:231], v[18:33]
	ds_read_b128 v[214:217], v248 offset:50752
	v_mfma_f32_32x32x16_bf16 v[34:49], v[206:209], v[228:231], v[34:49]
	s_waitcnt vmcnt(11)
	ds_write_b128 v250, v[10:13] offset:18432
	s_waitcnt lgkmcnt(7)
	v_mfma_f32_32x32x16_bf16 v[114:129], v[194:197], v[232:235], v[114:129]
	ds_read_b128 v[202:205], v249 offset:36960
	s_waitcnt lgkmcnt(6)
	v_mfma_f32_32x32x16_bf16 v[130:145], v[198:201], v[232:235], v[130:145]
	ds_read_b128 v[228:231], v248 offset:36960
	s_waitcnt lgkmcnt(6)
	v_mfma_f32_32x32x16_bf16 v[82:97], v[194:197], v[236:239], v[82:97]
	ds_read_b128 v[206:209], v249 offset:41568
	s_waitcnt vmcnt(10)
	ds_write_b128 v251, v[170:173] offset:18432
	v_mfma_f32_32x32x16_bf16 v[98:113], v[198:201], v[236:239], v[98:113]
	ds_read_b128 v[232:235], v248 offset:41568
	s_waitcnt lgkmcnt(8)
	v_mfma_f32_32x32x16_bf16 v[50:65], v[194:197], v[210:213], v[50:65]
	ds_read_b128 v[236:239], v248 offset:46176
	v_mfma_f32_32x32x16_bf16 v[66:81], v[198:201], v[210:213], v[66:81]
	s_waitcnt vmcnt(9)
	ds_write_b128 v250, v[14:17] offset:27648
	s_waitcnt lgkmcnt(8)
	v_mfma_f32_32x32x16_bf16 v[18:33], v[194:197], v[214:217], v[18:33]
	ds_read_b128 v[210:213], v248 offset:50784
	v_mfma_f32_32x32x16_bf16 v[34:49], v[198:201], v[214:217], v[34:49]
	s_waitcnt lgkmcnt(6)
	v_mfma_f32_32x32x16_bf16 v[114:129], v[202:205], v[228:231], v[114:129]
	s_waitcnt vmcnt(8)
	ds_write_b128 v251, v[174:177] offset:27648
	s_waitcnt lgkmcnt(6)
	v_mfma_f32_32x32x16_bf16 v[130:145], v[206:209], v[228:231], v[130:145]
	s_waitcnt lgkmcnt(4)
	v_mfma_f32_32x32x16_bf16 v[82:97], v[202:205], v[232:235], v[82:97]
	v_mfma_f32_32x32x16_bf16 v[98:113], v[206:209], v[232:235], v[98:113]
	s_waitcnt lgkmcnt(3)
	v_mfma_f32_32x32x16_bf16 v[50:65], v[202:205], v[236:239], v[50:65]
	v_mfma_f32_32x32x16_bf16 v[66:81], v[206:209], v[236:239], v[66:81]
	s_waitcnt lgkmcnt(1)
	v_mfma_f32_32x32x16_bf16 v[18:33], v[202:205], v[210:213], v[18:33]
	v_mfma_f32_32x32x16_bf16 v[34:49], v[206:209], v[210:213], v[34:49]
	s_waitcnt lgkmcnt(0)
	s_barrier
;     ...
;   for (int kt = 0; kt < nk; ++kt) {
;     __syncthreads();
;     if (kt + 1 < nk) {
;       u16* aw = As0 + ((kt + 1) & 1) * 256 * LD;
;       u16* bw = Bs0 + ((kt + 1) & 1) * 256 * LD;
; #pragma unroll
;       for (int i = 0; i < 4; ++i) { *(u32x4*)(aw + (srow + 64 * i) * LD + skc * 8) = ra[i]; *(u32x4*)(bw + (srow + 64 * i) * LD + skc * 8) = rb[i]; }
;     }
;     if (kt + 2 < nk) {
; #pragma unroll
;       for (int i = 0; i < 4; ++i) { ra[i] = *(const u32x4*)(Ag + (size_t)(64 * i) * K + (kt + 2) * 64); rb[i] = *(const u32x4*)(Bg[i] + (kt + 2) * 64); }
;     }
;     __builtin_amdgcn_sched_barrier(0);
;     const u16* as = As0 + (kt & 1) * 256 * LD + (wr * 128 + l31) * LD + h * 8;
;     const u16* bs = Bs0 + (kt & 1) * 256 * LD + (wc * 64 + l31) * LD + h * 8;
;     if (domma)
; #pragma unroll
;     for (int ks = 0; ks < 4; ++ks) {
;       bf16x8 wf[2], xf[4];
; #pragma unroll
;       for (int ct = 0; ct < 2; ++ct) wf[ct] = *(const bf16x8*)(bs + ct * 32 * LD + ks * 16);
; #pragma unroll
;       for (int tt = 0; tt < 4; ++tt) xf[tt] = *(const bf16x8*)(as + tt * 32 * LD + ks * 16);
; #pragma unroll
;       for (int ct = 0; ct < 2; ++ct)
; #pragma unroll
;         for (int tt = 0; tt < 4; ++tt) acc[ct][tt] = __builtin_amdgcn_mfma_f32_32x32x16_bf16(wf[ct], xf[tt], acc[ct][tt], 0, 0, 0);
;     }
;     __builtin_amdgcn_sched_barrier(0);
;   }
	ds_read_b128 v[194:197], v249
	ds_read_b128 v[210:213], v248
	ds_read_b128 v[198:201], v249 offset:4608
	ds_read_b128 v[214:217], v248 offset:4608
	ds_read_b128 v[228:231], v248 offset:9216
	ds_read_b128 v[232:235], v248 offset:13824
	s_waitcnt lgkmcnt(4)
	v_mfma_f32_32x32x16_bf16 v[114:129], v[194:197], v[210:213], v[114:129]
	ds_read_b128 v[202:205], v249 offset:32
	s_waitcnt lgkmcnt(4)
	v_mfma_f32_32x32x16_bf16 v[130:145], v[198:201], v[210:213], v[130:145]
	ds_read_b128 v[236:239], v248 offset:32
	s_waitcnt lgkmcnt(4)
	v_mfma_f32_32x32x16_bf16 v[82:97], v[194:197], v[214:217], v[82:97]
	ds_read_b128 v[206:209], v249 offset:4640
	v_mfma_f32_32x32x16_bf16 v[98:113], v[198:201], v[214:217], v[98:113]
	ds_read_b128 v[210:213], v248 offset:4640
	s_waitcnt vmcnt(7)
	ds_write_b128 v250, v[146:149] offset:36864
	s_waitcnt lgkmcnt(6)
	v_mfma_f32_32x32x16_bf16 v[50:65], v[194:197], v[228:231], v[50:65]
	ds_read_b128 v[214:217], v248 offset:9248
	v_mfma_f32_32x32x16_bf16 v[66:81], v[198:201], v[228:231], v[66:81]
	s_waitcnt lgkmcnt(6)
	v_mfma_f32_32x32x16_bf16 v[18:33], v[194:197], v[232:235], v[18:33]
	ds_read_b128 v[228:231], v248 offset:13856
	s_waitcnt vmcnt(6)
	ds_write_b128 v251, v[178:181] offset:36864
	v_mfma_f32_32x32x16_bf16 v[34:49], v[198:201], v[232:235], v[34:49]
	s_waitcnt lgkmcnt(6)
	v_mfma_f32_32x32x16_bf16 v[114:129], v[202:205], v[236:239], v[114:129]
	ds_read_b128 v[194:197], v249 offset:64
	s_waitcnt lgkmcnt(6)
	v_mfma_f32_32x32x16_bf16 v[130:145], v[206:209], v[236:239], v[130:145]
	ds_read_b128 v[232:235], v248 offset:64
	s_waitcnt vmcnt(5)
	ds_write_b128 v250, v[150:153] offset:46080
	s_waitcnt lgkmcnt(7)
	v_mfma_f32_32x32x16_bf16 v[82:97], v[202:205], v[210:213], v[82:97]
	ds_read_b128 v[198:201], v249 offset:4672
	v_mfma_f32_32x32x16_bf16 v[98:113], v[206:209], v[210:213], v[98:113]
	ds_read_b128 v[236:239], v248 offset:4672
	s_waitcnt lgkmcnt(7)
	v_mfma_f32_32x32x16_bf16 v[50:65], v[202:205], v[214:217], v[50:65]
	ds_read_b128 v[210:213], v248 offset:9280
	s_waitcnt vmcnt(4)
	ds_write_b128 v251, v[182:185] offset:46080
	v_mfma_f32_32x32x16_bf16 v[66:81], v[206:209], v[214:217], v[66:81]
	s_waitcnt lgkmcnt(8)
	v_mfma_f32_32x32x16_bf16 v[18:33], v[202:205], v[228:231], v[18:33]
	ds_read_b128 v[214:217], v248 offset:13888
	v_mfma_f32_32x32x16_bf16 v[34:49], v[206:209], v[228:231], v[34:49]
	s_waitcnt vmcnt(3)
	ds_write_b128 v250, v[154:157] offset:55296
	s_waitcnt lgkmcnt(7)
	v_mfma_f32_32x32x16_bf16 v[114:129], v[194:197], v[232:235], v[114:129]
	ds_read_b128 v[202:205], v249 offset:96
	s_waitcnt lgkmcnt(6)
	v_mfma_f32_32x32x16_bf16 v[130:145], v[198:201], v[232:235], v[130:145]
	ds_read_b128 v[228:231], v248 offset:96
	s_waitcnt lgkmcnt(6)
	v_mfma_f32_32x32x16_bf16 v[82:97], v[194:197], v[236:239], v[82:97]
	ds_read_b128 v[206:209], v249 offset:4704
	s_waitcnt vmcnt(2)
	ds_write_b128 v251, v[186:189] offset:55296
	v_mfma_f32_32x32x16_bf16 v[98:113], v[198:201], v[236:239], v[98:113]
	ds_read_b128 v[232:235], v248 offset:4704
	s_waitcnt lgkmcnt(8)
	v_mfma_f32_32x32x16_bf16 v[50:65], v[194:197], v[210:213], v[50:65]
	ds_read_b128 v[236:239], v248 offset:9312
	v_mfma_f32_32x32x16_bf16 v[66:81], v[198:201], v[210:213], v[66:81]
	s_waitcnt vmcnt(1)
	ds_write_b128 v250, v[158:161] offset:64512
	s_waitcnt lgkmcnt(8)
	v_mfma_f32_32x32x16_bf16 v[18:33], v[194:197], v[214:217], v[18:33]
	ds_read_b128 v[210:213], v248 offset:13920
	v_mfma_f32_32x32x16_bf16 v[34:49], v[198:201], v[214:217], v[34:49]
	s_waitcnt lgkmcnt(6)
	v_mfma_f32_32x32x16_bf16 v[114:129], v[202:205], v[228:231], v[114:129]
	s_waitcnt vmcnt(0)
	ds_write_b128 v251, v[190:193] offset:64512
	s_waitcnt lgkmcnt(6)
	v_mfma_f32_32x32x16_bf16 v[130:145], v[206:209], v[228:231], v[130:145]
	s_waitcnt lgkmcnt(4)
	v_mfma_f32_32x32x16_bf16 v[82:97], v[202:205], v[232:235], v[82:97]
	v_mfma_f32_32x32x16_bf16 v[98:113], v[206:209], v[232:235], v[98:113]
	s_waitcnt lgkmcnt(3)
	v_mfma_f32_32x32x16_bf16 v[50:65], v[202:205], v[236:239], v[50:65]
	v_mfma_f32_32x32x16_bf16 v[66:81], v[206:209], v[236:239], v[66:81]
	s_waitcnt lgkmcnt(1)
	v_mfma_f32_32x32x16_bf16 v[18:33], v[202:205], v[210:213], v[18:33]
	v_mfma_f32_32x32x16_bf16 v[34:49], v[206:209], v[210:213], v[34:49]
	s_waitcnt lgkmcnt(0)
	s_barrier
;     ...
;   for (int kt = 0; kt < nk; ++kt) {
;     __syncthreads();
;     if (kt + 1 < nk) {
;       u16* aw = As0 + ((kt + 1) & 1) * 256 * LD;
;       u16* bw = Bs0 + ((kt + 1) & 1) * 256 * LD;
; #pragma unroll
;       for (int i = 0; i < 4; ++i) { *(u32x4*)(aw + (srow + 64 * i) * LD + skc * 8) = ra[i]; *(u32x4*)(bw + (srow + 64 * i) * LD + skc * 8) = rb[i]; }
;     }
;     if (kt + 2 < nk) {
; #pragma unroll
;       for (int i = 0; i < 4; ++i) { ra[i] = *(const u32x4*)(Ag + (size_t)(64 * i) * K + (kt + 2) * 64); rb[i] = *(const u32x4*)(Bg[i] + (kt + 2) * 64); }
;     }
;     __builtin_amdgcn_sched_barrier(0);
;     const u16* as = As0 + (kt & 1) * 256 * LD + (wr * 128 + l31) * LD + h * 8;
;     const u16* bs = Bs0 + (kt & 1) * 256 * LD + (wc * 64 + l31) * LD + h * 8;
;     if (domma)
; #pragma unroll
;     for (int ks = 0; ks < 4; ++ks) {
;       bf16x8 wf[2], xf[4];
; #pragma unroll
;       for (int ct = 0; ct < 2; ++ct) wf[ct] = *(const bf16x8*)(bs + ct * 32 * LD + ks * 16);
; #pragma unroll
;       for (int tt = 0; tt < 4; ++tt) xf[tt] = *(const bf16x8*)(as + tt * 32 * LD + ks * 16);
; #pragma unroll
;       for (int ct = 0; ct < 2; ++ct)
; #pragma unroll
;         for (int tt = 0; tt < 4; ++tt) acc[ct][tt] = __builtin_amdgcn_mfma_f32_32x32x16_bf16(wf[ct], xf[tt], acc[ct][tt], 0, 0, 0);
;     }
;     ...
;       for (int tt = 0; tt < 4; ++tt) { tok[tt] = m0 + wr * 128 + tt * 32 + l31; rsv[tt] = p.rs[tok[tt]]; }
	ds_read_b128 v[194:197], v249 offset:36864
	ds_read_b128 v[210:213], v248 offset:36864
	ds_read_b128 v[198:201], v249 offset:41472
	ds_read_b128 v[214:217], v248 offset:41472
	ds_read_b128 v[228:231], v248 offset:46080
	ds_read_b128 v[232:235], v248 offset:50688
	s_waitcnt lgkmcnt(4)
	v_mfma_f32_32x32x16_bf16 v[114:129], v[194:197], v[210:213], v[114:129]
	ds_read_b128 v[202:205], v249 offset:36896
	s_waitcnt lgkmcnt(4)
	v_mfma_f32_32x32x16_bf16 v[130:145], v[198:201], v[210:213], v[130:145]
	ds_read_b128 v[236:239], v248 offset:36896
	s_waitcnt lgkmcnt(4)
	v_mfma_f32_32x32x16_bf16 v[82:97], v[194:197], v[214:217], v[82:97]
	ds_read_b128 v[206:209], v249 offset:41504
	s_add_i32 s31, s36, s35
	v_or_b32_e32 v12, s31, v225
	v_ashrrev_i32_e32 v13, 31, v12
	v_lshl_add_u64 v[14:15], v[12:13], 2, s[8:9]
	v_mfma_f32_32x32x16_bf16 v[98:113], v[198:201], v[214:217], v[98:113]
	ds_read_b128 v[210:213], v248 offset:41504
	s_waitcnt lgkmcnt(5)
	v_mfma_f32_32x32x16_bf16 v[50:65], v[194:197], v[228:231], v[50:65]
	ds_read_b128 v[214:217], v248 offset:46112
	global_load_dword v10, v[14:15], off
	global_load_dword v8, v[14:15], off offset:128
	global_load_dword v6, v[14:15], off offset:256
	global_load_dword v4, v[14:15], off offset:384
	v_mfma_f32_32x32x16_bf16 v[66:81], v[198:201], v[228:231], v[66:81]
	s_waitcnt lgkmcnt(5)
	v_mfma_f32_32x32x16_bf16 v[18:33], v[194:197], v[232:235], v[18:33]
	ds_read_b128 v[228:231], v248 offset:50720
	v_mfma_f32_32x32x16_bf16 v[34:49], v[198:201], v[232:235], v[34:49]
	s_waitcnt lgkmcnt(4)
	v_mfma_f32_32x32x16_bf16 v[114:129], v[202:205], v[236:239], v[114:129]
	ds_read_b128 v[194:197], v249 offset:36928
	s_waitcnt lgkmcnt(4)
	v_mfma_f32_32x32x16_bf16 v[130:145], v[206:209], v[236:239], v[130:145]
	ds_read_b128 v[232:235], v248 offset:36928
	s_waitcnt lgkmcnt(4)
	v_mfma_f32_32x32x16_bf16 v[82:97], v[202:205], v[210:213], v[82:97]
	ds_read_b128 v[198:201], v249 offset:41536
	v_mfma_f32_32x32x16_bf16 v[98:113], v[206:209], v[210:213], v[98:113]
	ds_read_b128 v[236:239], v248 offset:41536
	s_waitcnt lgkmcnt(5)
	v_mfma_f32_32x32x16_bf16 v[50:65], v[202:205], v[214:217], v[50:65]
	ds_read_b128 v[210:213], v248 offset:46144
	v_mfma_f32_32x32x16_bf16 v[66:81], v[206:209], v[214:217], v[66:81]
	s_waitcnt lgkmcnt(5)
	v_mfma_f32_32x32x16_bf16 v[18:33], v[202:205], v[228:231], v[18:33]
	ds_read_b128 v[214:217], v248 offset:50752
	v_mfma_f32_32x32x16_bf16 v[34:49], v[206:209], v[228:231], v[34:49]
	s_waitcnt lgkmcnt(4)
	v_mfma_f32_32x32x16_bf16 v[114:129], v[194:197], v[232:235], v[114:129]
	ds_read_b128 v[202:205], v249 offset:36960
	s_waitcnt lgkmcnt(4)
	v_mfma_f32_32x32x16_bf16 v[130:145], v[198:201], v[232:235], v[130:145]
	ds_read_b128 v[228:231], v248 offset:36960
	s_waitcnt lgkmcnt(4)
	v_mfma_f32_32x32x16_bf16 v[82:97], v[194:197], v[236:239], v[82:97]
	ds_read_b128 v[206:209], v249 offset:41568
	v_mfma_f32_32x32x16_bf16 v[98:113], v[198:201], v[236:239], v[98:113]
	ds_read_b128 v[232:235], v248 offset:41568
	s_waitcnt lgkmcnt(5)
	v_mfma_f32_32x32x16_bf16 v[50:65], v[194:197], v[210:213], v[50:65]
	ds_read_b128 v[236:239], v248 offset:46176
	v_mfma_f32_32x32x16_bf16 v[66:81], v[198:201], v[210:213], v[66:81]
	s_waitcnt lgkmcnt(5)
	v_mfma_f32_32x32x16_bf16 v[18:33], v[194:197], v[214:217], v[18:33]
	ds_read_b128 v[210:213], v248 offset:50784
	v_mfma_f32_32x32x16_bf16 v[34:49], v[198:201], v[214:217], v[34:49]
	s_waitcnt lgkmcnt(4)
	v_mfma_f32_32x32x16_bf16 v[114:129], v[202:205], v[228:231], v[114:129]
	s_waitcnt lgkmcnt(3)
	v_mfma_f32_32x32x16_bf16 v[130:145], v[206:209], v[228:231], v[130:145]
	s_waitcnt lgkmcnt(2)
	v_mfma_f32_32x32x16_bf16 v[82:97], v[202:205], v[232:235], v[82:97]
	v_mfma_f32_32x32x16_bf16 v[98:113], v[206:209], v[232:235], v[98:113]
	s_waitcnt lgkmcnt(1)
	v_mfma_f32_32x32x16_bf16 v[50:65], v[202:205], v[236:239], v[50:65]
	v_mfma_f32_32x32x16_bf16 v[66:81], v[206:209], v[236:239], v[66:81]
	s_waitcnt lgkmcnt(0)
	v_mfma_f32_32x32x16_bf16 v[18:33], v[202:205], v[210:213], v[18:33]
	v_mfma_f32_32x32x16_bf16 v[34:49], v[206:209], v[210:213], v[34:49]
	v_mov_b32_e32 v3, 0
	v_mov_b32_e32 v227, v223
	s_branch .LBB0_139
.Lp1_stage_only:
	v_lshrrev_b32_e32 v227, 3, v223
	v_lshlrev_b32_e32 v227, 11, v227
	v_lshlrev_b32_e32 v2, 4, v223
	v_and_b32_e32 v2, 0x70, v2
	v_or_b32_e32 v227, v227, v2
	s_lshl_b32 s6, s35, 11
	s_add_u32 s74, s16, s6
	s_addc_u32 s75, s17, 0
	s_add_u32 s76, s74, 0x20000
	s_addc_u32 s77, s75, 0
	s_add_u32 s78, s74, 0x40000
	s_addc_u32 s79, s75, 0
	s_add_u32 s80, s74, 0x60000
	s_addc_u32 s81, s75, 0
	s_lshl_b32 s6, s59, 11
	s_add_u32 s82, s18, s6
	s_addc_u32 s83, s19, 0
	s_add_u32 s84, s82, 0x20000
	s_addc_u32 s85, s83, 0
	s_add_u32 s86, s82, 0x40000
	s_addc_u32 s87, s83, 0
	s_add_u32 s92, s82, 0x60000
	s_addc_u32 s93, s83, 0
	global_load_dwordx4 v[2:5], v227, s[74:75] offset:256
	global_load_dwordx4 v[162:165], v227, s[82:83] offset:256
	global_load_dwordx4 v[6:9], v227, s[76:77] offset:256
	global_load_dwordx4 v[166:169], v227, s[84:85] offset:256
	global_load_dwordx4 v[10:13], v227, s[78:79] offset:256
	global_load_dwordx4 v[170:173], v227, s[86:87] offset:256
	global_load_dwordx4 v[14:17], v227, s[80:81] offset:256
	global_load_dwordx4 v[174:177], v227, s[92:93] offset:256
	global_load_dwordx4 v[146:149], v227, s[74:75] offset:384
	global_load_dwordx4 v[178:181], v227, s[82:83] offset:384
	global_load_dwordx4 v[150:153], v227, s[76:77] offset:384
	global_load_dwordx4 v[182:185], v227, s[84:85] offset:384
	global_load_dwordx4 v[154:157], v227, s[78:79] offset:384
	global_load_dwordx4 v[186:189], v227, s[86:87] offset:384
	global_load_dwordx4 v[158:161], v227, s[80:81] offset:384
	global_load_dwordx4 v[190:193], v227, s[92:93] offset:384
	s_waitcnt vmcnt(23)
	ds_write_b128 v251, v[36:39] offset:36864
	s_waitcnt vmcnt(22)
	ds_write_b128 v251, v[40:43] offset:46080
	s_waitcnt vmcnt(21)
	ds_write_b128 v251, v[44:47] offset:55296
	s_waitcnt vmcnt(20)
	ds_write_b128 v251, v[48:51] offset:64512
	s_waitcnt vmcnt(19)
	ds_write_b128 v250, v[52:55] offset:36864
	s_waitcnt vmcnt(18)
	ds_write_b128 v250, v[56:59] offset:46080
	s_waitcnt vmcnt(17)
	ds_write_b128 v250, v[60:63] offset:55296
	s_waitcnt vmcnt(16)
	ds_write_b128 v250, v[64:67] offset:64512
	s_waitcnt lgkmcnt(0)
	s_barrier
;     ...
;   for (int kt = 0; kt < nk; ++kt) {
;     __syncthreads();
;     if (kt + 1 < nk) {
;       u16* aw = As0 + ((kt + 1) & 1) * 256 * LD;
;       u16* bw = Bs0 + ((kt + 1) & 1) * 256 * LD;
; #pragma unroll
;       for (int i = 0; i < 4; ++i) { *(u32x4*)(aw + (srow + 64 * i) * LD + skc * 8) = ra[i]; *(u32x4*)(bw + (srow + 64 * i) * LD + skc * 8) = rb[i]; }
;     }
;     if (kt + 2 < nk) {
; #pragma unroll
;       for (int i = 0; i < 4; ++i) { ra[i] = *(const u32x4*)(Ag + (size_t)(64 * i) * K + (kt + 2) * 64); rb[i] = *(const u32x4*)(Bg[i] + (kt + 2) * 64); }
;     }
	s_waitcnt vmcnt(15)
	ds_write_b128 v250, v[2:5]
	global_load_dwordx4 v[2:5], v227, s[74:75] offset:512
	s_waitcnt vmcnt(15)
	ds_write_b128 v251, v[162:165]
	global_load_dwordx4 v[162:165], v227, s[82:83] offset:512
	s_waitcnt vmcnt(15)
	ds_write_b128 v250, v[6:9] offset:9216
	global_load_dwordx4 v[6:9], v227, s[76:77] offset:512
	s_waitcnt vmcnt(15)
	ds_write_b128 v251, v[166:169] offset:9216
	global_load_dwordx4 v[166:169], v227, s[84:85] offset:512
	s_waitcnt vmcnt(15)
	ds_write_b128 v250, v[10:13] offset:18432
	global_load_dwordx4 v[10:13], v227, s[78:79] offset:512
	s_waitcnt vmcnt(15)
	ds_write_b128 v251, v[170:173] offset:18432
	global_load_dwordx4 v[170:173], v227, s[86:87] offset:512
	s_waitcnt vmcnt(15)
	ds_write_b128 v250, v[14:17] offset:27648
	global_load_dwordx4 v[14:17], v227, s[80:81] offset:512
	s_waitcnt vmcnt(15)
	ds_write_b128 v251, v[174:177] offset:27648
	global_load_dwordx4 v[174:177], v227, s[92:93] offset:512
	s_waitcnt lgkmcnt(0)
	s_barrier
	s_waitcnt vmcnt(15)
	ds_write_b128 v250, v[146:149] offset:36864
	global_load_dwordx4 v[146:149], v227, s[74:75] offset:640
	s_waitcnt vmcnt(15)
	ds_write_b128 v251, v[178:181] offset:36864
	global_load_dwordx4 v[178:181], v227, s[82:83] offset:640
	s_waitcnt vmcnt(15)
	ds_write_b128 v250, v[150:153] offset:46080
	global_load_dwordx4 v[150:153], v227, s[76:77] offset:640
	s_waitcnt vmcnt(15)
	ds_write_b128 v251, v[182:185] offset:46080
	global_load_dwordx4 v[182:185], v227, s[84:85] offset:640
	s_waitcnt vmcnt(15)
	ds_write_b128 v250, v[154:157] offset:55296
	global_load_dwordx4 v[154:157], v227, s[78:79] offset:640
	s_waitcnt vmcnt(15)
	ds_write_b128 v251, v[186:189] offset:55296
	global_load_dwordx4 v[186:189], v227, s[86:87] offset:640
	s_waitcnt vmcnt(15)
	ds_write_b128 v250, v[158:161] offset:64512
	global_load_dwordx4 v[158:161], v227, s[80:81] offset:640
	s_waitcnt vmcnt(15)
	ds_write_b128 v251, v[190:193] offset:64512
	global_load_dwordx4 v[190:193], v227, s[92:93] offset:640
	s_waitcnt lgkmcnt(0)
	s_barrier
	s_waitcnt vmcnt(15)
	ds_write_b128 v250, v[2:5]
	global_load_dwordx4 v[2:5], v227, s[74:75] offset:768
	s_waitcnt vmcnt(15)
	ds_write_b128 v251, v[162:165]
	global_load_dwordx4 v[162:165], v227, s[82:83] offset:768
	s_waitcnt vmcnt(15)
	ds_write_b128 v250, v[6:9] offset:9216
	global_load_dwordx4 v[6:9], v227, s[76:77] offset:768
	s_waitcnt vmcnt(15)
	ds_write_b128 v251, v[166:169] offset:9216
	global_load_dwordx4 v[166:169], v227, s[84:85] offset:768
	s_waitcnt vmcnt(15)
	ds_write_b128 v250, v[10:13] offset:18432
	global_load_dwordx4 v[10:13], v227, s[78:79] offset:768
	s_waitcnt vmcnt(15)
	ds_write_b128 v251, v[170:173] offset:18432
	global_load_dwordx4 v[170:173], v227, s[86:87] offset:768
	s_waitcnt vmcnt(15)
	ds_write_b128 v250, v[14:17] offset:27648
	global_load_dwordx4 v[14:17], v227, s[80:81] offset:768
	s_waitcnt vmcnt(15)
	ds_write_b128 v251, v[174:177] offset:27648
	global_load_dwordx4 v[174:177], v227, s[92:93] offset:768
	s_waitcnt lgkmcnt(0)
	s_barrier
	s_waitcnt vmcnt(15)
	ds_write_b128 v250, v[146:149] offset:36864
	global_load_dwordx4 v[146:149], v227, s[74:75] offset:896
	s_waitcnt vmcnt(15)
	ds_write_b128 v251, v[178:181] offset:36864
	global_load_dwordx4 v[178:181], v227, s[82:83] offset:896
	s_waitcnt vmcnt(15)
	ds_write_b128 v250, v[150:153] offset:46080
	global_load_dwordx4 v[150:153], v227, s[76:77] offset:896
	s_waitcnt vmcnt(15)
	ds_write_b128 v251, v[182:185] offset:46080
	global_load_dwordx4 v[182:185], v227, s[84:85] offset:896
	s_waitcnt vmcnt(15)
	ds_write_b128 v250, v[154:157] offset:55296
	global_load_dwordx4 v[154:157], v227, s[78:79] offset:896
	s_waitcnt vmcnt(15)
	ds_write_b128 v251, v[186:189] offset:55296
	global_load_dwordx4 v[186:189], v227, s[86:87] offset:896
	s_waitcnt vmcnt(15)
	ds_write_b128 v250, v[158:161] offset:64512
	global_load_dwordx4 v[158:161], v227, s[80:81] offset:896
	s_waitcnt vmcnt(15)
	ds_write_b128 v251, v[190:193] offset:64512
	global_load_dwordx4 v[190:193], v227, s[92:93] offset:896
	s_waitcnt lgkmcnt(0)
	s_barrier
	s_waitcnt vmcnt(15)
	ds_write_b128 v250, v[2:5]
	global_load_dwordx4 v[2:5], v227, s[74:75] offset:1024
	s_waitcnt vmcnt(15)
	ds_write_b128 v251, v[162:165]
	global_load_dwordx4 v[162:165], v227, s[82:83] offset:1024
	s_waitcnt vmcnt(15)
	ds_write_b128 v250, v[6:9] offset:9216
	global_load_dwordx4 v[6:9], v227, s[76:77] offset:1024
	s_waitcnt vmcnt(15)
	ds_write_b128 v251, v[166:169] offset:9216
	global_load_dwordx4 v[166:169], v227, s[84:85] offset:1024
	s_waitcnt vmcnt(15)
	ds_write_b128 v250, v[10:13] offset:18432
	global_load_dwordx4 v[10:13], v227, s[78:79] offset:1024
	s_waitcnt vmcnt(15)
	ds_write_b128 v251, v[170:173] offset:18432
	global_load_dwordx4 v[170:173], v227, s[86:87] offset:1024
	s_waitcnt vmcnt(15)
	ds_write_b128 v250, v[14:17] offset:27648
	global_load_dwordx4 v[14:17], v227, s[80:81] offset:1024
	s_waitcnt vmcnt(15)
	ds_write_b128 v251, v[174:177] offset:27648
	global_load_dwordx4 v[174:177], v227, s[92:93] offset:1024
	s_waitcnt lgkmcnt(0)
	s_barrier
	s_waitcnt vmcnt(15)
	ds_write_b128 v250, v[146:149] offset:36864
	global_load_dwordx4 v[146:149], v227, s[74:75] offset:1152
	s_waitcnt vmcnt(15)
	ds_write_b128 v251, v[178:181] offset:36864
	global_load_dwordx4 v[178:181], v227, s[82:83] offset:1152
	s_waitcnt vmcnt(15)
	ds_write_b128 v250, v[150:153] offset:46080
	global_load_dwordx4 v[150:153], v227, s[76:77] offset:1152
	s_waitcnt vmcnt(15)
	ds_write_b128 v251, v[182:185] offset:46080
	global_load_dwordx4 v[182:185], v227, s[84:85] offset:1152
	s_waitcnt vmcnt(15)
	ds_write_b128 v250, v[154:157] offset:55296
	global_load_dwordx4 v[154:157], v227, s[78:79] offset:1152
	s_waitcnt vmcnt(15)
	ds_write_b128 v251, v[186:189] offset:55296
	global_load_dwordx4 v[186:189], v227, s[86:87] offset:1152
	s_waitcnt vmcnt(15)
	ds_write_b128 v250, v[158:161] offset:64512
	global_load_dwordx4 v[158:161], v227, s[80:81] offset:1152
	s_waitcnt vmcnt(15)
	ds_write_b128 v251, v[190:193] offset:64512
	global_load_dwordx4 v[190:193], v227, s[92:93] offset:1152
	s_waitcnt lgkmcnt(0)
	s_barrier
;     ...
;   for (int kt = 0; kt < nk; ++kt) {
;     __syncthreads();
;     if (kt + 1 < nk) {
;       u16* aw = As0 + ((kt + 1) & 1) * 256 * LD;
;       u16* bw = Bs0 + ((kt + 1) & 1) * 256 * LD;
; #pragma unroll
;       for (int i = 0; i < 4; ++i) { *(u32x4*)(aw + (srow + 64 * i) * LD + skc * 8) = ra[i]; *(u32x4*)(bw + (srow + 64 * i) * LD + skc * 8) = rb[i]; }
;     }
;     if (kt + 2 < nk) {
; #pragma unroll
;       for (int i = 0; i < 4; ++i) { ra[i] = *(const u32x4*)(Ag + (size_t)(64 * i) * K + (kt + 2) * 64); rb[i] = *(const u32x4*)(Bg[i] + (kt + 2) * 64); }
;     }
	s_waitcnt vmcnt(15)
	ds_write_b128 v250, v[2:5]
	global_load_dwordx4 v[2:5], v227, s[74:75] offset:1280
	s_waitcnt vmcnt(15)
	ds_write_b128 v251, v[162:165]
	global_load_dwordx4 v[162:165], v227, s[82:83] offset:1280
	s_waitcnt vmcnt(15)
	ds_write_b128 v250, v[6:9] offset:9216
	global_load_dwordx4 v[6:9], v227, s[76:77] offset:1280
	s_waitcnt vmcnt(15)
	ds_write_b128 v251, v[166:169] offset:9216
	global_load_dwordx4 v[166:169], v227, s[84:85] offset:1280
	s_waitcnt vmcnt(15)
	ds_write_b128 v250, v[10:13] offset:18432
	global_load_dwordx4 v[10:13], v227, s[78:79] offset:1280
	s_waitcnt vmcnt(15)
	ds_write_b128 v251, v[170:173] offset:18432
	global_load_dwordx4 v[170:173], v227, s[86:87] offset:1280
	s_waitcnt vmcnt(15)
	ds_write_b128 v250, v[14:17] offset:27648
	global_load_dwordx4 v[14:17], v227, s[80:81] offset:1280
	s_waitcnt vmcnt(15)
	ds_write_b128 v251, v[174:177] offset:27648
	global_load_dwordx4 v[174:177], v227, s[92:93] offset:1280
	s_waitcnt lgkmcnt(0)
	s_barrier
	s_waitcnt vmcnt(15)
	ds_write_b128 v250, v[146:149] offset:36864
	global_load_dwordx4 v[146:149], v227, s[74:75] offset:1408
	s_waitcnt vmcnt(15)
	ds_write_b128 v251, v[178:181] offset:36864
	global_load_dwordx4 v[178:181], v227, s[82:83] offset:1408
	s_waitcnt vmcnt(15)
	ds_write_b128 v250, v[150:153] offset:46080
	global_load_dwordx4 v[150:153], v227, s[76:77] offset:1408
	s_waitcnt vmcnt(15)
	ds_write_b128 v251, v[182:185] offset:46080
	global_load_dwordx4 v[182:185], v227, s[84:85] offset:1408
	s_waitcnt vmcnt(15)
	ds_write_b128 v250, v[154:157] offset:55296
	global_load_dwordx4 v[154:157], v227, s[78:79] offset:1408
	s_waitcnt vmcnt(15)
	ds_write_b128 v251, v[186:189] offset:55296
	global_load_dwordx4 v[186:189], v227, s[86:87] offset:1408
	s_waitcnt vmcnt(15)
	ds_write_b128 v250, v[158:161] offset:64512
	global_load_dwordx4 v[158:161], v227, s[80:81] offset:1408
	s_waitcnt vmcnt(15)
	ds_write_b128 v251, v[190:193] offset:64512
	global_load_dwordx4 v[190:193], v227, s[92:93] offset:1408
	s_waitcnt lgkmcnt(0)
	s_barrier
	s_waitcnt vmcnt(15)
	ds_write_b128 v250, v[2:5]
	global_load_dwordx4 v[2:5], v227, s[74:75] offset:1536
	s_waitcnt vmcnt(15)
	ds_write_b128 v251, v[162:165]
	global_load_dwordx4 v[162:165], v227, s[82:83] offset:1536
	s_waitcnt vmcnt(15)
	ds_write_b128 v250, v[6:9] offset:9216
	global_load_dwordx4 v[6:9], v227, s[76:77] offset:1536
	s_waitcnt vmcnt(15)
	ds_write_b128 v251, v[166:169] offset:9216
	global_load_dwordx4 v[166:169], v227, s[84:85] offset:1536
	s_waitcnt vmcnt(15)
	ds_write_b128 v250, v[10:13] offset:18432
	global_load_dwordx4 v[10:13], v227, s[78:79] offset:1536
	s_waitcnt vmcnt(15)
	ds_write_b128 v251, v[170:173] offset:18432
	global_load_dwordx4 v[170:173], v227, s[86:87] offset:1536
	s_waitcnt vmcnt(15)
	ds_write_b128 v250, v[14:17] offset:27648
	global_load_dwordx4 v[14:17], v227, s[80:81] offset:1536
	s_waitcnt vmcnt(15)
	ds_write_b128 v251, v[174:177] offset:27648
	global_load_dwordx4 v[174:177], v227, s[92:93] offset:1536
	s_waitcnt lgkmcnt(0)
	s_barrier
	s_waitcnt vmcnt(15)
	ds_write_b128 v250, v[146:149] offset:36864
	global_load_dwordx4 v[146:149], v227, s[74:75] offset:1664
	s_waitcnt vmcnt(15)
	ds_write_b128 v251, v[178:181] offset:36864
	global_load_dwordx4 v[178:181], v227, s[82:83] offset:1664
	s_waitcnt vmcnt(15)
	ds_write_b128 v250, v[150:153] offset:46080
	global_load_dwordx4 v[150:153], v227, s[76:77] offset:1664
	s_waitcnt vmcnt(15)
	ds_write_b128 v251, v[182:185] offset:46080
	global_load_dwordx4 v[182:185], v227, s[84:85] offset:1664
	s_waitcnt vmcnt(15)
	ds_write_b128 v250, v[154:157] offset:55296
	global_load_dwordx4 v[154:157], v227, s[78:79] offset:1664
	s_waitcnt vmcnt(15)
	ds_write_b128 v251, v[186:189] offset:55296
	global_load_dwordx4 v[186:189], v227, s[86:87] offset:1664
	s_waitcnt vmcnt(15)
	ds_write_b128 v250, v[158:161] offset:64512
	global_load_dwordx4 v[158:161], v227, s[80:81] offset:1664
	s_waitcnt vmcnt(15)
	ds_write_b128 v251, v[190:193] offset:64512
	global_load_dwordx4 v[190:193], v227, s[92:93] offset:1664
	s_waitcnt lgkmcnt(0)
	s_barrier
;     ...
;   for (int kt = 0; kt < nk; ++kt) {
;     __syncthreads();
;     if (kt + 1 < nk) {
;       u16* aw = As0 + ((kt + 1) & 1) * 256 * LD;
;       u16* bw = Bs0 + ((kt + 1) & 1) * 256 * LD;
; #pragma unroll
;       for (int i = 0; i < 4; ++i) { *(u32x4*)(aw + (srow + 64 * i) * LD + skc * 8) = ra[i]; *(u32x4*)(bw + (srow + 64 * i) * LD + skc * 8) = rb[i]; }
;     }
;     if (kt + 2 < nk) {
; #pragma unroll
;       for (int i = 0; i < 4; ++i) { ra[i] = *(const u32x4*)(Ag + (size_t)(64 * i) * K + (kt + 2) * 64); rb[i] = *(const u32x4*)(Bg[i] + (kt + 2) * 64); }
;     }
;     ...
;     gemm_tile(p.xb, p.winT, DM, mt * 256, nt * 256, INW, lds, [&](f32x16 (&acc)[2][4], int m0, int n0, int wr, int wc, int l31, int h) {
;       float rsv[4]; int tok[4];
; #pragma unroll
;       for (int tt = 0; tt < 4; ++tt) { tok[tt] = m0 + wr * 128 + tt * 32 + l31; rsv[tt] = p.rs[tok[tt]]; }
;       if (mode == 1) {
;         float sacc = 0.f;
; #pragma unroll
;         for (int ct = 0; ct < 2; ++ct)
; #pragma unroll
;           for (int tt = 0; tt < 4; ++tt)
; #pragma unroll
;             for (int r = 0; r < 16; ++r) sacc += acc[ct][tt][r];
;         if (sacc == 123.456f) p.rs[tok[0]] = sacc;
;         return;
;       }
;       const int nw = n0 + wc * 64;
;       const int lane = h * 32 + l31;
;       u16* stg = (u16*)lds + (wr * 4 + wc) * (128 * LD);
;       float* red = (float*)(lds + 8 * 128 * LD * 2);
;       const int bq = m0 >> 12, pos0 = (m0 & 4095) + wr * 128;
;       auto flush_rows = [&](u16* gbase, size_t ldd) {
; #pragma unroll
;         for (int it = 0; it < 16; ++it) {
;           const int r = it * 8 + (lane >> 3), ch = lane & 7;
;           *(u32x4*)(gbase + (size_t)r * ldd + ch * 8) = *(const u32x4*)(stg + r * LD + ch * 8);
;         }
;       };
;       if (n0 < 1024) {
	s_waitcnt vmcnt(15)
	ds_write_b128 v250, v[2:5]
	global_load_dwordx4 v[2:5], v227, s[74:75] offset:1792
	s_waitcnt vmcnt(15)
	ds_write_b128 v251, v[162:165]
	global_load_dwordx4 v[162:165], v227, s[82:83] offset:1792
	s_waitcnt vmcnt(15)
	ds_write_b128 v250, v[6:9] offset:9216
	global_load_dwordx4 v[6:9], v227, s[76:77] offset:1792
	s_waitcnt vmcnt(15)
	ds_write_b128 v251, v[166:169] offset:9216
	global_load_dwordx4 v[166:169], v227, s[84:85] offset:1792
	s_waitcnt vmcnt(15)
	ds_write_b128 v250, v[10:13] offset:18432
	global_load_dwordx4 v[10:13], v227, s[78:79] offset:1792
	s_waitcnt vmcnt(15)
	ds_write_b128 v251, v[170:173] offset:18432
	global_load_dwordx4 v[170:173], v227, s[86:87] offset:1792
	s_waitcnt vmcnt(15)
	ds_write_b128 v250, v[14:17] offset:27648
	global_load_dwordx4 v[14:17], v227, s[80:81] offset:1792
	s_waitcnt vmcnt(15)
	ds_write_b128 v251, v[174:177] offset:27648
	global_load_dwordx4 v[174:177], v227, s[92:93] offset:1792
	s_waitcnt lgkmcnt(0)
	s_barrier
	s_waitcnt vmcnt(15)
	ds_write_b128 v250, v[146:149] offset:36864
	global_load_dwordx4 v[146:149], v227, s[74:75] offset:1920
	s_waitcnt vmcnt(15)
	ds_write_b128 v251, v[178:181] offset:36864
	global_load_dwordx4 v[178:181], v227, s[82:83] offset:1920
	s_waitcnt vmcnt(15)
	ds_write_b128 v250, v[150:153] offset:46080
	global_load_dwordx4 v[150:153], v227, s[76:77] offset:1920
	s_waitcnt vmcnt(15)
	ds_write_b128 v251, v[182:185] offset:46080
	global_load_dwordx4 v[182:185], v227, s[84:85] offset:1920
	s_waitcnt vmcnt(15)
	ds_write_b128 v250, v[154:157] offset:55296
	global_load_dwordx4 v[154:157], v227, s[78:79] offset:1920
	s_waitcnt vmcnt(15)
	ds_write_b128 v251, v[186:189] offset:55296
	global_load_dwordx4 v[186:189], v227, s[86:87] offset:1920
	s_waitcnt vmcnt(15)
	ds_write_b128 v250, v[158:161] offset:64512
	global_load_dwordx4 v[158:161], v227, s[80:81] offset:1920
	s_waitcnt vmcnt(15)
	ds_write_b128 v251, v[190:193] offset:64512
	global_load_dwordx4 v[190:193], v227, s[92:93] offset:1920
	s_waitcnt lgkmcnt(0)
	s_barrier
	s_waitcnt vmcnt(15)
	ds_write_b128 v250, v[2:5]
	s_waitcnt vmcnt(14)
	ds_write_b128 v251, v[162:165]
	s_waitcnt vmcnt(13)
	ds_write_b128 v250, v[6:9] offset:9216
	s_waitcnt vmcnt(12)
	ds_write_b128 v251, v[166:169] offset:9216
	s_waitcnt vmcnt(11)
	ds_write_b128 v250, v[10:13] offset:18432
	s_waitcnt vmcnt(10)
	ds_write_b128 v251, v[170:173] offset:18432
	s_waitcnt vmcnt(9)
	ds_write_b128 v250, v[14:17] offset:27648
	s_waitcnt vmcnt(8)
	ds_write_b128 v251, v[174:177] offset:27648
	s_waitcnt lgkmcnt(0)
	s_barrier
	s_waitcnt vmcnt(7)
	ds_write_b128 v250, v[146:149] offset:36864
	s_waitcnt vmcnt(6)
	ds_write_b128 v251, v[178:181] offset:36864
	s_waitcnt vmcnt(5)
	ds_write_b128 v250, v[150:153] offset:46080
	s_waitcnt vmcnt(4)
	ds_write_b128 v251, v[182:185] offset:46080
	s_waitcnt vmcnt(3)
	ds_write_b128 v250, v[154:157] offset:55296
	s_waitcnt vmcnt(2)
	ds_write_b128 v251, v[186:189] offset:55296
	s_waitcnt vmcnt(1)
	ds_write_b128 v250, v[158:161] offset:64512
	s_waitcnt vmcnt(0)
	ds_write_b128 v251, v[190:193] offset:64512
	s_waitcnt lgkmcnt(0)
	s_barrier
	s_add_i32 s31, s36, s35
	v_or_b32_e32 v12, s31, v225
	v_ashrrev_i32_e32 v13, 31, v12
	v_lshl_add_u64 v[14:15], v[12:13], 2, s[8:9]
	global_load_dword v10, v[14:15], off
	global_load_dword v8, v[14:15], off offset:128
	global_load_dword v6, v[14:15], off offset:256
	global_load_dword v4, v[14:15], off offset:384
	v_mov_b32_e32 v3, 0
	v_mov_b32_e32 v227, v223
	s_branch .LBB0_139
.LBB0_139:
	v_lshlrev_b32_e32 v5, 3, v247
	s_add_i32 s31, s36, s35
	v_or_b32_e32 v12, s31, v225
	v_ashrrev_i32_e32 v13, 31, v12
	v_lshl_add_u64 v[14:15], v[12:13], 2, s[8:9]
	s_barrier
	s_lshl_b32 s6, s37, 2
	s_add_i32 s6, s20, s6
	s_mulk_i32 s6, 0x4800
	s_add_i32 s7, s6, 0
	s_and_b32 s6, s35, 0xf00
	s_add_i32 s64, s61, s59
	s_ashr_i32 s63, s34, 4
	s_add_i32 s30, s36, s6
	v_and_b32_e32 v147, 63, v227
	s_cmp_gt_i32 s62, 3
	s_mov_b64 s[34:35], -1
	s_cbranch_scc0 .LBB0_150
	s_cmpk_gt_i32 s64, 0x5ff
	s_cbranch_scc0 .LBB0_147
	s_cmpk_gt_u32 s64, 0x107f
	s_cbranch_scc1 .LBB0_146
	s_cmpk_lt_u32 s64, 0x800
	s_cbranch_scc1 .LBB0_144
	s_cmpk_gt_u32 s64, 0xe7f
	s_cselect_b64 s[36:37], -1, 0
	s_and_b64 s[34:35], s[36:37], exec
	s_cselect_b32 s20, s53, 0xb8
	s_cselect_b32 s34, s47, 0x680
	s_cselect_b32 s35, s52, 0xfffff800
	s_mov_b64 s[38:39], s[20:21]
	s_branch .LBB0_145
